# loop-invariant ds_read temp addresses hoisted out of the P1/P5/P6 K-loops (R phases now issue no VALU instructions)
# speedup vs baseline: 1.0098x; 1.0032x over previous
; #define PG8_STAGE(bufoff, gbase, voff) do { _Pragma("unroll") for (int _i = 0; _i < 2; ++_i) \
;         __builtin_amdgcn_global_load_lds((const unsigned*)((const char*)(gbase) + (voff)[_i]), (LAS unsigned*)(lds + (bufoff) + ldsw + _i * 8192), 16, 0, 0); } while (0)
; #define PG8_LDA(dst, b, h) do { _Pragma("unroll") for (int m = 0; m < 4; ++m) _Pragma("unroll") for (int k = 0; k < 2; ++k) dst[m][k] = *(const LAS bf16x8*)(lds + PG8_SA(b, h) + aoff + m * 2048 + k * 1024); } while (0)
; #define PG8_LDB(dst, b, h) do { _Pragma("unroll") for (int n = 0; n < 2; ++n) _Pragma("unroll") for (int k = 0; k < 2; ++k) dst[n][k] = *(const LAS bf16x8*)(lds + PG8_SB(b, h) + boff + n * 2048 + k * 1024); } while (0)
; #define PG8_MMA(ai, bj, At, Bt) do { __builtin_amdgcn_s_setprio(3); _Pragma("unroll") for (int m = 0; m < 4; ++m) _Pragma("unroll") for (int n = 0; n < 2; ++n) _Pragma("unroll") for (int k = 0; k < 2; ++k) \
;         acc[ai][bj][m][n] = __builtin_amdgcn_mfma_f32_16x16x32_bf16(Bt[n][k], At[m][k], acc[ai][bj][m][n], 0, 0, 0); __builtin_amdgcn_s_setprio(0); } while (0)
; #define PG8_WAIT_V(n) asm volatile("s_waitcnt vmcnt(" #n ")" ::: "memory")
; #define PG8_WAIT_L(n) asm volatile("s_waitcnt lgkmcnt(" #n ")" ::: "memory")
; #define PG8_BAR __builtin_amdgcn_s_barrier()
; #define PG8_SCHED __builtin_amdgcn_sched_barrier(0)
; template <class Epi, class Sched, bool ALIGN_EPI = false, bool SP2 = false>
; __device__ __forceinline__ void gemm_phase(LAS unsigned char* lds, const Gemm g, const Sched& S, const Epi& E) {
;     ...
;             PG8_LDB(B0, 0, 0); PG8_LDB(B1, 0, 1); PG8_SCHED; PG8_LDA(At, 0, 0); PG8_STAGE(PG8_SA(1, 1), a1 + hsA, voffA);
;             PG8_WAIT_V(8); PG8_WAIT_L(0); PG8_BAR; PG8_MMA(0, 0, At, B0); PG8_MMA(0, 1, At, B1); PG8_BAR; PG8_SCHED;
;     ...
; #pragma unroll
;         for (int a = 0; a < 2; ++a)
; #pragma unroll
;             for (int b = 0; b < 2; ++b)
; #pragma unroll
;                 for (int m = 0; m < 4; ++m)
; #pragma unroll
;                     for (int n = 0; n < 2; ++n) acc[a][b][m][n] = (f32x4){0.f, 0.f, 0.f, 0.f};
;         cur = nxt; cA = nA; cB = nB; ++ui;
.LBB0_63:
	s_add_u32 s4, s62, 0x104080
	s_addc_u32 s5, s63, 0
	s_add_u32 s89, s6, 0x100
	v_mov_b32_e32 v0, 0
	s_addc_u32 s90, s7, 0
	s_mov_b32 s91, -2
	s_waitcnt lgkmcnt(0)
	v_mov_b32_e32 v1, v0
	v_mov_b32_e32 v2, v0
	v_mov_b32_e32 v3, v0
	v_mov_b32_e32 v4, v0
	v_mov_b32_e32 v5, v0
	v_mov_b32_e32 v6, v0
	v_mov_b32_e32 v7, v0
	v_mov_b32_e32 v16, v0
	v_mov_b32_e32 v17, v0
	v_mov_b32_e32 v18, v0
	v_mov_b32_e32 v19, v0
	v_mov_b32_e32 v20, v0
	v_mov_b32_e32 v21, v0
	v_mov_b32_e32 v22, v0
	v_mov_b32_e32 v23, v0
	v_mov_b32_e32 v32, v0
	v_mov_b32_e32 v33, v0
	v_mov_b32_e32 v34, v0
	v_mov_b32_e32 v35, v0
	v_mov_b32_e32 v36, v0
	v_mov_b32_e32 v37, v0
	v_mov_b32_e32 v38, v0
	v_mov_b32_e32 v39, v0
	v_mov_b32_e32 v48, v0
	v_mov_b32_e32 v49, v0
	v_mov_b32_e32 v50, v0
	v_mov_b32_e32 v51, v0
	v_mov_b32_e32 v52, v0
	v_mov_b32_e32 v53, v0
	v_mov_b32_e32 v54, v0
	v_mov_b32_e32 v55, v0
	v_mov_b32_e32 v8, v0
	v_mov_b32_e32 v9, v0
	v_mov_b32_e32 v10, v0
	v_mov_b32_e32 v11, v0
	v_mov_b32_e32 v12, v0
	v_mov_b32_e32 v13, v0
	v_mov_b32_e32 v14, v0
	v_mov_b32_e32 v15, v0
	v_mov_b32_e32 v24, v0
	v_mov_b32_e32 v25, v0
	v_mov_b32_e32 v26, v0
	v_mov_b32_e32 v27, v0
	v_mov_b32_e32 v28, v0
	v_mov_b32_e32 v29, v0
	v_mov_b32_e32 v30, v0
	v_mov_b32_e32 v31, v0
	v_mov_b32_e32 v40, v0
	v_mov_b32_e32 v41, v0
	v_mov_b32_e32 v42, v0
	v_mov_b32_e32 v43, v0
	v_mov_b32_e32 v44, v0
	v_mov_b32_e32 v45, v0
	v_mov_b32_e32 v46, v0
	v_mov_b32_e32 v47, v0
	v_mov_b32_e32 v56, v0
	v_mov_b32_e32 v57, v0
	v_mov_b32_e32 v58, v0
	v_mov_b32_e32 v59, v0
	v_mov_b32_e32 v60, v0
	v_mov_b32_e32 v61, v0
	v_mov_b32_e32 v62, v0
	v_mov_b32_e32 v63, v0
	v_mov_b32_e32 v64, v0
	v_mov_b32_e32 v65, v0
	v_mov_b32_e32 v66, v0
	v_mov_b32_e32 v67, v0
	v_mov_b32_e32 v68, v0
	v_mov_b32_e32 v69, v0
	v_mov_b32_e32 v70, v0
	v_mov_b32_e32 v71, v0
	v_mov_b32_e32 v80, v0
	v_mov_b32_e32 v81, v0
	v_mov_b32_e32 v82, v0
	v_mov_b32_e32 v83, v0
	v_mov_b32_e32 v84, v0
	v_mov_b32_e32 v85, v0
	v_mov_b32_e32 v86, v0
	v_mov_b32_e32 v87, v0
	v_mov_b32_e32 v96, v0
	v_mov_b32_e32 v97, v0
	v_mov_b32_e32 v98, v0
	v_mov_b32_e32 v99, v0
	v_mov_b32_e32 v100, v0
	v_mov_b32_e32 v101, v0
	v_mov_b32_e32 v102, v0
	v_mov_b32_e32 v103, v0
	v_mov_b32_e32 v112, v0
	v_mov_b32_e32 v113, v0
	v_mov_b32_e32 v114, v0
	v_mov_b32_e32 v115, v0
	v_mov_b32_e32 v116, v0
	v_mov_b32_e32 v117, v0
	v_mov_b32_e32 v118, v0
	v_mov_b32_e32 v119, v0
	v_mov_b32_e32 v72, v0
	v_mov_b32_e32 v73, v0
	v_mov_b32_e32 v74, v0
	v_mov_b32_e32 v75, v0
	v_mov_b32_e32 v76, v0
	v_mov_b32_e32 v77, v0
	v_mov_b32_e32 v78, v0
	v_mov_b32_e32 v79, v0
	v_mov_b32_e32 v88, v0
	v_mov_b32_e32 v89, v0
	v_mov_b32_e32 v90, v0
	v_mov_b32_e32 v91, v0
	v_mov_b32_e32 v92, v0
	v_mov_b32_e32 v93, v0
	v_mov_b32_e32 v94, v0
	v_mov_b32_e32 v95, v0
	v_mov_b32_e32 v104, v0
	v_mov_b32_e32 v105, v0
	v_mov_b32_e32 v106, v0
	v_mov_b32_e32 v107, v0
	v_mov_b32_e32 v108, v0
	v_mov_b32_e32 v109, v0
	v_mov_b32_e32 v110, v0
	v_mov_b32_e32 v111, v0
	v_mov_b32_e32 v120, v0
	v_mov_b32_e32 v121, v0
	v_mov_b32_e32 v122, v0
	v_mov_b32_e32 v123, v0
	v_mov_b32_e32 v124, v0
	v_mov_b32_e32 v125, v0
	v_mov_b32_e32 v126, v0
	v_mov_b32_e32 v127, v0
	v_add_u32_e32 v246, 0x18000, v156
	v_xor_b32_e32 v247, 64, v246
	v_add_u32_e32 v248, 0x1c000, v156
	v_xor_b32_e32 v249, 64, v248
.LBB0_64:
	ds_read_b128 v[128:131], v158
	ds_read_b128 v[150:153], v251
	ds_read_b128 v[166:169], v158 offset:2048
	ds_read_b128 v[170:173], v251 offset:2048
	ds_read_b128 v[174:177], v159
	ds_read_b128 v[178:181], v252
	ds_read_b128 v[182:185], v159 offset:2048
	ds_read_b128 v[186:189], v252 offset:2048
	s_add_u32 s6, s4, 0xffefc080
	s_addc_u32 s7, s5, -1
	s_cmp_eq_u32 s91, 60
	s_cselect_b32 s63, s59, s7
	s_cselect_b32 s62, s58, s6
	s_cselect_b32 s7, s61, s90
	s_cselect_b32 s6, s60, s89
	s_sub_u32 s100, s4, 0x104000
	s_subb_u32 s101, s5, 0
	s_mov_b32 m0, s76
	s_nop 0
	global_load_lds_dwordx4 v132, s[100:101]
	s_mov_b32 m0, s77
	s_nop 0
	global_load_lds_dwordx4 v136, s[100:101]
	s_add_i32 m0, s68, 0xc000
	ds_read_b128 v[190:193], v160
	ds_read_b128 v[194:197], v250
	ds_read_b128 v[198:201], v160 offset:2048
	ds_read_b128 v[206:209], v250 offset:2048
	ds_read_b128 v[210:213], v160 offset:4096
	ds_read_b128 v[214:217], v250 offset:4096
	ds_read_b128 v[218:221], v160 offset:6144
	ds_read_b128 v[222:225], v250 offset:6144
	global_load_lds_dwordx4 v142, s[4:5]
	s_add_i32 m0, s68, 0xe000
	s_nop 0
	global_load_lds_dwordx4 v144, s[4:5]
	s_waitcnt vmcnt(8)
	s_waitcnt lgkmcnt(0)
	s_setprio 2
	s_barrier
	v_mfma_f32_16x16x32_bf16 v[124:127], v[128:131], v[190:193], v[124:127]
	v_mfma_f32_16x16x32_bf16 v[124:127], v[150:153], v[194:197], v[124:127]
	v_mfma_f32_16x16x32_bf16 v[120:123], v[166:169], v[190:193], v[120:123]
	v_mfma_f32_16x16x32_bf16 v[120:123], v[170:173], v[194:197], v[120:123]
	v_mfma_f32_16x16x32_bf16 v[108:111], v[128:131], v[198:201], v[108:111]
	v_mfma_f32_16x16x32_bf16 v[108:111], v[150:153], v[206:209], v[108:111]
	v_mfma_f32_16x16x32_bf16 v[104:107], v[166:169], v[198:201], v[104:107]
	v_mfma_f32_16x16x32_bf16 v[104:107], v[170:173], v[206:209], v[104:107]
	v_mfma_f32_16x16x32_bf16 v[92:95], v[128:131], v[210:213], v[92:95]
	v_mfma_f32_16x16x32_bf16 v[92:95], v[150:153], v[214:217], v[92:95]
	v_mfma_f32_16x16x32_bf16 v[88:91], v[166:169], v[210:213], v[88:91]
	v_mfma_f32_16x16x32_bf16 v[88:91], v[170:173], v[214:217], v[88:91]
	v_mfma_f32_16x16x32_bf16 v[76:79], v[128:131], v[218:221], v[76:79]
	v_mfma_f32_16x16x32_bf16 v[76:79], v[150:153], v[222:225], v[76:79]
	v_mfma_f32_16x16x32_bf16 v[72:75], v[166:169], v[218:221], v[72:75]
	v_mfma_f32_16x16x32_bf16 v[72:75], v[170:173], v[222:225], v[72:75]
	s_setprio 0
	s_setprio 2
	v_mfma_f32_16x16x32_bf16 v[116:119], v[174:177], v[190:193], v[116:119]
	v_mfma_f32_16x16x32_bf16 v[116:119], v[178:181], v[194:197], v[116:119]
	v_mfma_f32_16x16x32_bf16 v[112:115], v[182:185], v[190:193], v[112:115]
	v_mfma_f32_16x16x32_bf16 v[112:115], v[186:189], v[194:197], v[112:115]
	v_mfma_f32_16x16x32_bf16 v[100:103], v[174:177], v[198:201], v[100:103]
	v_mfma_f32_16x16x32_bf16 v[100:103], v[178:181], v[206:209], v[100:103]
	v_mfma_f32_16x16x32_bf16 v[96:99], v[182:185], v[198:201], v[96:99]
	v_mfma_f32_16x16x32_bf16 v[96:99], v[186:189], v[206:209], v[96:99]
	v_mfma_f32_16x16x32_bf16 v[84:87], v[174:177], v[210:213], v[84:87]
	v_mfma_f32_16x16x32_bf16 v[84:87], v[178:181], v[214:217], v[84:87]
	v_mfma_f32_16x16x32_bf16 v[80:83], v[182:185], v[210:213], v[80:83]
	v_mfma_f32_16x16x32_bf16 v[80:83], v[186:189], v[214:217], v[80:83]
	v_mfma_f32_16x16x32_bf16 v[68:71], v[174:177], v[218:221], v[68:71]
	v_mfma_f32_16x16x32_bf16 v[68:71], v[178:181], v[222:225], v[68:71]
	v_mfma_f32_16x16x32_bf16 v[64:67], v[182:185], v[218:221], v[64:67]
	s_setprio 3
	s_barrier
; #define PG8_STAGE(bufoff, gbase, voff) do { _Pragma("unroll") for (int _i = 0; _i < 2; ++_i) \
;         __builtin_amdgcn_global_load_lds((const unsigned*)((const char*)(gbase) + (voff)[_i]), (LAS unsigned*)(lds + (bufoff) + ldsw + _i * 8192), 16, 0, 0); } while (0)
; #define PG8_LDA(dst, b, h) do { _Pragma("unroll") for (int m = 0; m < 4; ++m) _Pragma("unroll") for (int k = 0; k < 2; ++k) dst[m][k] = *(const LAS bf16x8*)(lds + PG8_SA(b, h) + aoff + m * 2048 + k * 1024); } while (0)
; #define PG8_LDB(dst, b, h) do { _Pragma("unroll") for (int n = 0; n < 2; ++n) _Pragma("unroll") for (int k = 0; k < 2; ++k) dst[n][k] = *(const LAS bf16x8*)(lds + PG8_SB(b, h) + boff + n * 2048 + k * 1024); } while (0)
; #define PG8_MMA(ai, bj, At, Bt) do { __builtin_amdgcn_s_setprio(3); _Pragma("unroll") for (int m = 0; m < 4; ++m) _Pragma("unroll") for (int n = 0; n < 2; ++n) _Pragma("unroll") for (int k = 0; k < 2; ++k) \
;         acc[ai][bj][m][n] = __builtin_amdgcn_mfma_f32_16x16x32_bf16(Bt[n][k], At[m][k], acc[ai][bj][m][n], 0, 0, 0); __builtin_amdgcn_s_setprio(0); } while (0)
; #define PG8_WAIT_V(n) asm volatile("s_waitcnt vmcnt(" #n ")" ::: "memory")
; #define PG8_WAIT_L(n) asm volatile("s_waitcnt lgkmcnt(" #n ")" ::: "memory")
; #define PG8_BAR __builtin_amdgcn_s_barrier()
; #define PG8_SCHED __builtin_amdgcn_sched_barrier(0)
; template <class Epi, class Sched, bool ALIGN_EPI = false, bool SP2 = false>
; __device__ __forceinline__ void gemm_phase(LAS unsigned char* lds, const Gemm g, const Sched& S, const Epi& E) {
;     ...
;             PG8_WAIT_V(8); PG8_WAIT_L(0); PG8_BAR; PG8_MMA(0, 0, At, B0); PG8_MMA(0, 1, At, B1); PG8_BAR; PG8_SCHED;
;             PG8_LDA(At, 0, 1); PG8_STAGE(PG8_SB(0, 0), b2, voffB); PG8_STAGE(PG8_SB(0, 1), b2 + hsB, voffB); PG8_STAGE(PG8_SA(0, 0), a2, voffA);
;             PG8_WAIT_V(8); PG8_WAIT_L(0); PG8_BAR; PG8_MMA(1, 0, At, B0); PG8_MMA(1, 1, At, B1); PG8_BAR; PG8_SCHED;
;             PG8_LDB(B0, 1, 0); PG8_LDB(B1, 1, 1); PG8_SCHED; PG8_LDA(At, 1, 0); PG8_STAGE(PG8_SA(0, 1), a2 + hsA, voffA);
	v_mfma_f32_16x16x32_bf16 v[64:67], v[186:189], v[222:225], v[64:67]
	s_setprio 0
	s_add_i32 s92, s82, s67
	s_mov_b32 m0, s92
	ds_read_b128 v[190:193], v160 offset:16384
	ds_read_b128 v[194:197], v250 offset:16384
	ds_read_b128 v[198:201], v160 offset:18432
	ds_read_b128 v[206:209], v250 offset:18432
	ds_read_b128 v[210:213], v160 offset:20480
	ds_read_b128 v[214:217], v250 offset:20480
	ds_read_b128 v[218:221], v160 offset:22528
	ds_read_b128 v[222:225], v250 offset:22528
	global_load_lds_dwordx4 v134, s[6:7]
	s_add_i32 m0, s92, 0x2000
	s_add_u32 s92, s6, 0x41000
	s_addc_u32 s93, s7, 0
	s_add_i32 s94, s83, s67
	global_load_lds_dwordx4 v138, s[6:7]
	s_mov_b32 m0, s94
	s_nop 0
	global_load_lds_dwordx4 v134, s[92:93]
	s_add_i32 m0, s94, 0x2000
	s_nop 0
	global_load_lds_dwordx4 v138, s[92:93]
	s_waitcnt vmcnt(6)
	s_waitcnt lgkmcnt(0)
	s_setprio 2
	s_barrier
	v_mfma_f32_16x16x32_bf16 v[60:63], v[128:131], v[190:193], v[60:63]
	v_mfma_f32_16x16x32_bf16 v[60:63], v[150:153], v[194:197], v[60:63]
	v_mfma_f32_16x16x32_bf16 v[56:59], v[166:169], v[190:193], v[56:59]
	v_mfma_f32_16x16x32_bf16 v[56:59], v[170:173], v[194:197], v[56:59]
	v_mfma_f32_16x16x32_bf16 v[44:47], v[128:131], v[198:201], v[44:47]
	v_mfma_f32_16x16x32_bf16 v[44:47], v[150:153], v[206:209], v[44:47]
	v_mfma_f32_16x16x32_bf16 v[40:43], v[166:169], v[198:201], v[40:43]
	v_mfma_f32_16x16x32_bf16 v[40:43], v[170:173], v[206:209], v[40:43]
	v_mfma_f32_16x16x32_bf16 v[28:31], v[128:131], v[210:213], v[28:31]
	v_mfma_f32_16x16x32_bf16 v[28:31], v[150:153], v[214:217], v[28:31]
	v_mfma_f32_16x16x32_bf16 v[24:27], v[166:169], v[210:213], v[24:27]
	v_mfma_f32_16x16x32_bf16 v[24:27], v[170:173], v[214:217], v[24:27]
	v_mfma_f32_16x16x32_bf16 v[12:15], v[128:131], v[218:221], v[12:15]
	v_mfma_f32_16x16x32_bf16 v[12:15], v[150:153], v[222:225], v[12:15]
	v_mfma_f32_16x16x32_bf16 v[8:11], v[166:169], v[218:221], v[8:11]
	v_mfma_f32_16x16x32_bf16 v[8:11], v[170:173], v[222:225], v[8:11]
	s_setprio 0
	s_setprio 2
	v_mfma_f32_16x16x32_bf16 v[52:55], v[174:177], v[190:193], v[52:55]
	v_mfma_f32_16x16x32_bf16 v[52:55], v[178:181], v[194:197], v[52:55]
	v_mfma_f32_16x16x32_bf16 v[48:51], v[182:185], v[190:193], v[48:51]
	v_mfma_f32_16x16x32_bf16 v[48:51], v[186:189], v[194:197], v[48:51]
	v_mfma_f32_16x16x32_bf16 v[36:39], v[174:177], v[198:201], v[36:39]
	v_mfma_f32_16x16x32_bf16 v[36:39], v[178:181], v[206:209], v[36:39]
	v_mfma_f32_16x16x32_bf16 v[32:35], v[182:185], v[198:201], v[32:35]
	v_mfma_f32_16x16x32_bf16 v[32:35], v[186:189], v[206:209], v[32:35]
	v_mfma_f32_16x16x32_bf16 v[20:23], v[174:177], v[210:213], v[20:23]
	v_mfma_f32_16x16x32_bf16 v[20:23], v[178:181], v[214:217], v[20:23]
	v_mfma_f32_16x16x32_bf16 v[16:19], v[182:185], v[210:213], v[16:19]
	v_mfma_f32_16x16x32_bf16 v[16:19], v[186:189], v[214:217], v[16:19]
	v_mfma_f32_16x16x32_bf16 v[4:7], v[174:177], v[218:221], v[4:7]
	v_mfma_f32_16x16x32_bf16 v[4:7], v[178:181], v[222:225], v[4:7]
	v_mfma_f32_16x16x32_bf16 v[0:3], v[182:185], v[218:221], v[0:3]
	s_setprio 3
	s_barrier
	v_mfma_f32_16x16x32_bf16 v[0:3], v[186:189], v[222:225], v[0:3]
	s_setprio 0
	s_add_i32 s92, 0, 0x18000
	s_add_i32 s93, 0, 0x1c000
	ds_read_b128 v[128:131], v246
	ds_read_b128 v[150:153], v247
	ds_read_b128 v[166:169], v246 offset:2048
	ds_read_b128 v[170:173], v247 offset:2048
	ds_read_b128 v[174:177], v248
	ds_read_b128 v[178:181], v249
	ds_read_b128 v[182:185], v248 offset:2048
	ds_read_b128 v[186:189], v249 offset:2048
	s_mov_b32 m0, s68
	s_nop 0
	global_load_lds_dwordx4 v132, s[62:63]
	s_mov_b32 m0, s69
	s_nop 0
	global_load_lds_dwordx4 v136, s[62:63]
	s_add_u32 s62, s62, 0x104000
	s_addc_u32 s63, s63, 0
	s_mov_b32 m0, s70
	ds_read_b128 v[190:193], v160 offset:32768
	ds_read_b128 v[194:197], v250 offset:32768
	ds_read_b128 v[198:201], v160 offset:34816
	ds_read_b128 v[206:209], v250 offset:34816
	ds_read_b128 v[210:213], v160 offset:36864
	ds_read_b128 v[214:217], v250 offset:36864
	ds_read_b128 v[218:221], v160 offset:38912
	ds_read_b128 v[222:225], v250 offset:38912
	global_load_lds_dwordx4 v132, s[62:63]
	s_mov_b32 m0, s71
	s_nop 0
	global_load_lds_dwordx4 v136, s[62:63]
	s_waitcnt vmcnt(8)
	s_waitcnt lgkmcnt(0)
	s_setprio 2
	s_barrier
; #define PG8_STAGE(bufoff, gbase, voff) do { _Pragma("unroll") for (int _i = 0; _i < 2; ++_i) \
;         __builtin_amdgcn_global_load_lds((const unsigned*)((const char*)(gbase) + (voff)[_i]), (LAS unsigned*)(lds + (bufoff) + ldsw + _i * 8192), 16, 0, 0); } while (0)
; #define PG8_LDA(dst, b, h) do { _Pragma("unroll") for (int m = 0; m < 4; ++m) _Pragma("unroll") for (int k = 0; k < 2; ++k) dst[m][k] = *(const LAS bf16x8*)(lds + PG8_SA(b, h) + aoff + m * 2048 + k * 1024); } while (0)
; #define PG8_MMA(ai, bj, At, Bt) do { __builtin_amdgcn_s_setprio(3); _Pragma("unroll") for (int m = 0; m < 4; ++m) _Pragma("unroll") for (int n = 0; n < 2; ++n) _Pragma("unroll") for (int k = 0; k < 2; ++k) \
;         acc[ai][bj][m][n] = __builtin_amdgcn_mfma_f32_16x16x32_bf16(Bt[n][k], At[m][k], acc[ai][bj][m][n], 0, 0, 0); __builtin_amdgcn_s_setprio(0); } while (0)
; #define PG8_WAIT_V(n) asm volatile("s_waitcnt vmcnt(" #n ")" ::: "memory")
; #define PG8_WAIT_L(n) asm volatile("s_waitcnt lgkmcnt(" #n ")" ::: "memory")
; #define PG8_BAR __builtin_amdgcn_s_barrier()
; #define PG8_SCHED __builtin_amdgcn_sched_barrier(0)
; template <class Epi, class Sched, bool ALIGN_EPI = false, bool SP2 = false>
; __device__ __forceinline__ void gemm_phase(LAS unsigned char* lds, const Gemm g, const Sched& S, const Epi& E) {
;     ...
;             PG8_WAIT_V(8); PG8_WAIT_L(0); PG8_BAR; PG8_MMA(0, 0, At, B0); PG8_MMA(0, 1, At, B1); PG8_BAR; PG8_SCHED;
;             PG8_LDA(At, 1, 1); PG8_STAGE(PG8_SB(1, 0), b3, voffB); PG8_STAGE(PG8_SB(1, 1), b3 + hsB, voffB); PG8_STAGE(PG8_SA(1, 0), a3, voffA);
;             PG8_WAIT_V(8); PG8_WAIT_L(0); PG8_BAR; PG8_MMA(1, 0, At, B0); PG8_MMA(1, 1, At, B1); PG8_BAR; PG8_SCHED;
;     ...
;         if constexpr (ALIGN_EPI) { if (wr == 0) PG8_BAR; }
	v_mfma_f32_16x16x32_bf16 v[124:127], v[128:131], v[190:193], v[124:127]
	v_mfma_f32_16x16x32_bf16 v[124:127], v[150:153], v[194:197], v[124:127]
	v_mfma_f32_16x16x32_bf16 v[120:123], v[166:169], v[190:193], v[120:123]
	v_mfma_f32_16x16x32_bf16 v[120:123], v[170:173], v[194:197], v[120:123]
	v_mfma_f32_16x16x32_bf16 v[108:111], v[128:131], v[198:201], v[108:111]
	v_mfma_f32_16x16x32_bf16 v[108:111], v[150:153], v[206:209], v[108:111]
	v_mfma_f32_16x16x32_bf16 v[104:107], v[166:169], v[198:201], v[104:107]
	v_mfma_f32_16x16x32_bf16 v[104:107], v[170:173], v[206:209], v[104:107]
	v_mfma_f32_16x16x32_bf16 v[92:95], v[128:131], v[210:213], v[92:95]
	v_mfma_f32_16x16x32_bf16 v[92:95], v[150:153], v[214:217], v[92:95]
	v_mfma_f32_16x16x32_bf16 v[88:91], v[166:169], v[210:213], v[88:91]
	v_mfma_f32_16x16x32_bf16 v[88:91], v[170:173], v[214:217], v[88:91]
	v_mfma_f32_16x16x32_bf16 v[76:79], v[128:131], v[218:221], v[76:79]
	v_mfma_f32_16x16x32_bf16 v[76:79], v[150:153], v[222:225], v[76:79]
	v_mfma_f32_16x16x32_bf16 v[72:75], v[166:169], v[218:221], v[72:75]
	v_mfma_f32_16x16x32_bf16 v[72:75], v[170:173], v[222:225], v[72:75]
	s_setprio 0
	s_setprio 2
	v_mfma_f32_16x16x32_bf16 v[116:119], v[174:177], v[190:193], v[116:119]
	v_mfma_f32_16x16x32_bf16 v[116:119], v[178:181], v[194:197], v[116:119]
	v_mfma_f32_16x16x32_bf16 v[112:115], v[182:185], v[190:193], v[112:115]
	v_mfma_f32_16x16x32_bf16 v[112:115], v[186:189], v[194:197], v[112:115]
	v_mfma_f32_16x16x32_bf16 v[100:103], v[174:177], v[198:201], v[100:103]
	v_mfma_f32_16x16x32_bf16 v[100:103], v[178:181], v[206:209], v[100:103]
	v_mfma_f32_16x16x32_bf16 v[96:99], v[182:185], v[198:201], v[96:99]
	v_mfma_f32_16x16x32_bf16 v[96:99], v[186:189], v[206:209], v[96:99]
	v_mfma_f32_16x16x32_bf16 v[84:87], v[174:177], v[210:213], v[84:87]
	v_mfma_f32_16x16x32_bf16 v[84:87], v[178:181], v[214:217], v[84:87]
	v_mfma_f32_16x16x32_bf16 v[80:83], v[182:185], v[210:213], v[80:83]
	v_mfma_f32_16x16x32_bf16 v[80:83], v[186:189], v[214:217], v[80:83]
	v_mfma_f32_16x16x32_bf16 v[68:71], v[174:177], v[218:221], v[68:71]
	v_mfma_f32_16x16x32_bf16 v[68:71], v[178:181], v[222:225], v[68:71]
	v_mfma_f32_16x16x32_bf16 v[64:67], v[182:185], v[218:221], v[64:67]
	s_setprio 3
	s_barrier
	v_mfma_f32_16x16x32_bf16 v[64:67], v[186:189], v[222:225], v[64:67]
	s_setprio 0
	s_add_i32 s62, s92, s67
	s_add_u32 s100, s6, s46
	s_addc_u32 s101, s7, s47
	s_mov_b32 m0, s62
	ds_read_b128 v[190:193], v160 offset:49152
	ds_read_b128 v[194:197], v250 offset:49152
	ds_read_b128 v[198:201], v160 offset:51200
	ds_read_b128 v[206:209], v250 offset:51200
	ds_read_b128 v[210:213], v160 offset:53248
	ds_read_b128 v[214:217], v250 offset:53248
	ds_read_b128 v[218:221], v160 offset:55296
	ds_read_b128 v[222:225], v250 offset:55296
	global_load_lds_dwordx4 v134, s[100:101]
	s_add_i32 m0, s62, 0x2000
	s_add_u32 s6, s6, 0x41080
	s_addc_u32 s7, s7, 0
	s_add_i32 s62, s93, s67
	global_load_lds_dwordx4 v138, s[100:101]
	s_mov_b32 m0, s62
	s_nop 0
	global_load_lds_dwordx4 v134, s[6:7]
	s_add_i32 m0, s62, 0x2000
	s_nop 0
	global_load_lds_dwordx4 v138, s[6:7]
	s_waitcnt vmcnt(6)
	s_waitcnt lgkmcnt(0)
	s_setprio 2
	s_barrier
	v_mfma_f32_16x16x32_bf16 v[60:63], v[128:131], v[190:193], v[60:63]
	v_mfma_f32_16x16x32_bf16 v[60:63], v[150:153], v[194:197], v[60:63]
	v_mfma_f32_16x16x32_bf16 v[56:59], v[166:169], v[190:193], v[56:59]
	v_mfma_f32_16x16x32_bf16 v[56:59], v[170:173], v[194:197], v[56:59]
	v_mfma_f32_16x16x32_bf16 v[44:47], v[128:131], v[198:201], v[44:47]
	v_mfma_f32_16x16x32_bf16 v[44:47], v[150:153], v[206:209], v[44:47]
	v_mfma_f32_16x16x32_bf16 v[40:43], v[166:169], v[198:201], v[40:43]
	v_mfma_f32_16x16x32_bf16 v[40:43], v[170:173], v[206:209], v[40:43]
	v_mfma_f32_16x16x32_bf16 v[28:31], v[128:131], v[210:213], v[28:31]
	v_mfma_f32_16x16x32_bf16 v[28:31], v[150:153], v[214:217], v[28:31]
	v_mfma_f32_16x16x32_bf16 v[24:27], v[166:169], v[210:213], v[24:27]
	v_mfma_f32_16x16x32_bf16 v[24:27], v[170:173], v[214:217], v[24:27]
	v_mfma_f32_16x16x32_bf16 v[12:15], v[128:131], v[218:221], v[12:15]
	v_mfma_f32_16x16x32_bf16 v[12:15], v[150:153], v[222:225], v[12:15]
	v_mfma_f32_16x16x32_bf16 v[8:11], v[166:169], v[218:221], v[8:11]
	v_mfma_f32_16x16x32_bf16 v[8:11], v[170:173], v[222:225], v[8:11]
	s_setprio 0
	s_setprio 2
	v_mfma_f32_16x16x32_bf16 v[52:55], v[174:177], v[190:193], v[52:55]
	v_mfma_f32_16x16x32_bf16 v[52:55], v[178:181], v[194:197], v[52:55]
	v_mfma_f32_16x16x32_bf16 v[48:51], v[182:185], v[190:193], v[48:51]
	v_mfma_f32_16x16x32_bf16 v[48:51], v[186:189], v[194:197], v[48:51]
	v_mfma_f32_16x16x32_bf16 v[36:39], v[174:177], v[198:201], v[36:39]
	v_mfma_f32_16x16x32_bf16 v[36:39], v[178:181], v[206:209], v[36:39]
	v_mfma_f32_16x16x32_bf16 v[32:35], v[182:185], v[198:201], v[32:35]
	v_mfma_f32_16x16x32_bf16 v[32:35], v[186:189], v[206:209], v[32:35]
	v_mfma_f32_16x16x32_bf16 v[20:23], v[174:177], v[210:213], v[20:23]
	v_mfma_f32_16x16x32_bf16 v[20:23], v[178:181], v[214:217], v[20:23]
	v_mfma_f32_16x16x32_bf16 v[16:19], v[182:185], v[210:213], v[16:19]
	v_mfma_f32_16x16x32_bf16 v[16:19], v[186:189], v[214:217], v[16:19]
	v_mfma_f32_16x16x32_bf16 v[4:7], v[174:177], v[218:221], v[4:7]
	v_mfma_f32_16x16x32_bf16 v[4:7], v[178:181], v[222:225], v[4:7]
	v_mfma_f32_16x16x32_bf16 v[0:3], v[182:185], v[218:221], v[0:3]
	s_setprio 3
	s_barrier
	v_mfma_f32_16x16x32_bf16 v[0:3], v[186:189], v[222:225], v[0:3]
	s_setprio 0
	s_add_i32 s91, s91, 2
	s_add_u32 s4, s4, 0x100
	s_addc_u32 s5, s5, 0
	s_add_u32 s89, s89, 0x100
	s_addc_u32 s90, s90, 0
	s_cmp_gt_u32 s91, 61
	s_cbranch_scc0 .LBB0_64
	s_and_b64 vcc, exec, s[50:51]
	s_cbranch_vccz .LBB0_67
	s_barrier

; #define PG8_STAGE(bufoff, gbase, voff) do { _Pragma("unroll") for (int _i = 0; _i < 2; ++_i) \
;         __builtin_amdgcn_global_load_lds((const unsigned*)((const char*)(gbase) + (voff)[_i]), (LAS unsigned*)(lds + (bufoff) + ldsw + _i * 8192), 16, 0, 0); } while (0)
; #define PG8_LDA(dst, b, h) do { _Pragma("unroll") for (int m = 0; m < 4; ++m) _Pragma("unroll") for (int k = 0; k < 2; ++k) dst[m][k] = *(const LAS bf16x8*)(lds + PG8_SA(b, h) + aoff + m * 2048 + k * 1024); } while (0)
; #define PG8_LDB(dst, b, h) do { _Pragma("unroll") for (int n = 0; n < 2; ++n) _Pragma("unroll") for (int k = 0; k < 2; ++k) dst[n][k] = *(const LAS bf16x8*)(lds + PG8_SB(b, h) + boff + n * 2048 + k * 1024); } while (0)
; #define PG8_MMA(ai, bj, At, Bt) do { __builtin_amdgcn_s_setprio(3); _Pragma("unroll") for (int m = 0; m < 4; ++m) _Pragma("unroll") for (int n = 0; n < 2; ++n) _Pragma("unroll") for (int k = 0; k < 2; ++k) \
;         acc[ai][bj][m][n] = __builtin_amdgcn_mfma_f32_16x16x32_bf16(Bt[n][k], At[m][k], acc[ai][bj][m][n], 0, 0, 0); __builtin_amdgcn_s_setprio(0); } while (0)
; #define PG8_WAIT_V(n) asm volatile("s_waitcnt vmcnt(" #n ")" ::: "memory")
; #define PG8_WAIT_L(n) asm volatile("s_waitcnt lgkmcnt(" #n ")" ::: "memory")
; #define PG8_BAR __builtin_amdgcn_s_barrier()
; #define PG8_SCHED __builtin_amdgcn_sched_barrier(0)
; template <class Epi, class Sched, bool ALIGN_EPI = false, bool SP2 = false>
; __device__ __forceinline__ void gemm_phase(LAS unsigned char* lds, const Gemm g, const Sched& S, const Epi& E) {
;     ...
;             PG8_LDB(B0, 0, 0); PG8_LDB(B1, 0, 1); PG8_SCHED; PG8_LDA(At, 0, 0); PG8_STAGE(PG8_SA(1, 1), a1 + hsA, voffA);
;             PG8_WAIT_V(8); PG8_WAIT_L(0); PG8_BAR; PG8_MMA(0, 0, At, B0); PG8_MMA(0, 1, At, B1); PG8_BAR; PG8_SCHED;
;     ...
; #pragma unroll
;         for (int a = 0; a < 2; ++a)
; #pragma unroll
;             for (int b = 0; b < 2; ++b)
; #pragma unroll
;                 for (int m = 0; m < 4; ++m)
; #pragma unroll
;                     for (int n = 0; n < 2; ++n) acc[a][b][m][n] = (f32x4){0.f, 0.f, 0.f, 0.f};
;         cur = nxt; cA = nA; cB = nB; ++ui;
.LBB0_308:
	s_add_u32 s4, s26, 0x104080
	s_addc_u32 s5, s27, 0
	s_add_u32 s71, s24, 0x100
	v_mov_b32_e32 v0, 0
	s_addc_u32 s72, s25, 0
	s_mov_b32 s73, -2
	v_mov_b32_e32 v1, v0
	v_mov_b32_e32 v2, v0
	v_mov_b32_e32 v3, v0
	v_mov_b32_e32 v4, v0
	v_mov_b32_e32 v5, v0
	v_mov_b32_e32 v6, v0
	v_mov_b32_e32 v7, v0
	v_mov_b32_e32 v16, v0
	v_mov_b32_e32 v17, v0
	v_mov_b32_e32 v18, v0
	v_mov_b32_e32 v19, v0
	v_mov_b32_e32 v20, v0
	v_mov_b32_e32 v21, v0
	v_mov_b32_e32 v22, v0
	v_mov_b32_e32 v23, v0
	v_mov_b32_e32 v32, v0
	v_mov_b32_e32 v33, v0
	v_mov_b32_e32 v34, v0
	v_mov_b32_e32 v35, v0
	v_mov_b32_e32 v36, v0
	v_mov_b32_e32 v37, v0
	v_mov_b32_e32 v38, v0
	v_mov_b32_e32 v39, v0
	v_mov_b32_e32 v48, v0
	v_mov_b32_e32 v49, v0
	v_mov_b32_e32 v50, v0
	v_mov_b32_e32 v51, v0
	v_mov_b32_e32 v52, v0
	v_mov_b32_e32 v53, v0
	v_mov_b32_e32 v54, v0
	v_mov_b32_e32 v55, v0
	v_mov_b32_e32 v8, v0
	v_mov_b32_e32 v9, v0
	v_mov_b32_e32 v10, v0
	v_mov_b32_e32 v11, v0
	v_mov_b32_e32 v12, v0
	v_mov_b32_e32 v13, v0
	v_mov_b32_e32 v14, v0
	v_mov_b32_e32 v15, v0
	v_mov_b32_e32 v24, v0
	v_mov_b32_e32 v25, v0
	v_mov_b32_e32 v26, v0
	v_mov_b32_e32 v27, v0
	v_mov_b32_e32 v28, v0
	v_mov_b32_e32 v29, v0
	v_mov_b32_e32 v30, v0
	v_mov_b32_e32 v31, v0
	v_mov_b32_e32 v40, v0
	v_mov_b32_e32 v41, v0
	v_mov_b32_e32 v42, v0
	v_mov_b32_e32 v43, v0
	v_mov_b32_e32 v44, v0
	v_mov_b32_e32 v45, v0
	v_mov_b32_e32 v46, v0
	v_mov_b32_e32 v47, v0
	v_mov_b32_e32 v56, v0
	v_mov_b32_e32 v57, v0
	v_mov_b32_e32 v58, v0
	v_mov_b32_e32 v59, v0
	v_mov_b32_e32 v60, v0
	v_mov_b32_e32 v61, v0
	v_mov_b32_e32 v62, v0
	v_mov_b32_e32 v63, v0
	v_mov_b32_e32 v64, v0
	v_mov_b32_e32 v65, v0
	v_mov_b32_e32 v66, v0
	v_mov_b32_e32 v67, v0
	v_mov_b32_e32 v68, v0
	v_mov_b32_e32 v69, v0
	v_mov_b32_e32 v70, v0
	v_mov_b32_e32 v71, v0
	v_mov_b32_e32 v80, v0
	v_mov_b32_e32 v81, v0
	v_mov_b32_e32 v82, v0
	v_mov_b32_e32 v83, v0
	v_mov_b32_e32 v84, v0
	v_mov_b32_e32 v85, v0
	v_mov_b32_e32 v86, v0
	v_mov_b32_e32 v87, v0
	v_mov_b32_e32 v96, v0
	v_mov_b32_e32 v97, v0
	v_mov_b32_e32 v98, v0
	v_mov_b32_e32 v99, v0
	v_mov_b32_e32 v100, v0
	v_mov_b32_e32 v101, v0
	v_mov_b32_e32 v102, v0
	v_mov_b32_e32 v103, v0
	v_mov_b32_e32 v116, v0
	v_mov_b32_e32 v117, v0
	v_mov_b32_e32 v118, v0
	v_mov_b32_e32 v119, v0
	v_mov_b32_e32 v120, v0
	v_mov_b32_e32 v121, v0
	v_mov_b32_e32 v122, v0
	v_mov_b32_e32 v123, v0
	v_mov_b32_e32 v72, v0
	v_mov_b32_e32 v73, v0
	v_mov_b32_e32 v74, v0
	v_mov_b32_e32 v75, v0
	v_mov_b32_e32 v76, v0
	v_mov_b32_e32 v77, v0
	v_mov_b32_e32 v78, v0
	v_mov_b32_e32 v79, v0
	v_mov_b32_e32 v88, v0
	v_mov_b32_e32 v89, v0
	v_mov_b32_e32 v90, v0
	v_mov_b32_e32 v91, v0
	v_mov_b32_e32 v92, v0
	v_mov_b32_e32 v93, v0
	v_mov_b32_e32 v94, v0
	v_mov_b32_e32 v95, v0
	v_mov_b32_e32 v104, v0
	v_mov_b32_e32 v105, v0
	v_mov_b32_e32 v106, v0
	v_mov_b32_e32 v107, v0
	v_mov_b32_e32 v108, v0
	v_mov_b32_e32 v109, v0
	v_mov_b32_e32 v110, v0
	v_mov_b32_e32 v111, v0
	v_mov_b32_e32 v124, v0
	v_mov_b32_e32 v125, v0
	v_mov_b32_e32 v126, v0
	v_mov_b32_e32 v127, v0
	v_mov_b32_e32 v128, v0
	v_mov_b32_e32 v129, v0
	v_mov_b32_e32 v130, v0
	v_mov_b32_e32 v131, v0
	v_add_u32_e32 v246, 0x18000, v173
	v_xor_b32_e32 v247, 64, v246
	v_add_u32_e32 v248, 0x1c000, v173
	v_xor_b32_e32 v249, 64, v248
.LBB0_309:
	ds_read_b128 v[112:115], v175
	ds_read_b128 v[132:135], v251
	ds_read_b128 v[136:139], v175 offset:2048
	ds_read_b128 v[140:143], v251 offset:2048
	ds_read_b128 v[144:147], v176
	ds_read_b128 v[148:151], v252
	ds_read_b128 v[184:187], v176 offset:2048
	ds_read_b128 v[188:191], v252 offset:2048
	s_add_u32 s24, s4, 0xffefc080
	s_addc_u32 s25, s5, -1
	s_cmp_eq_u32 s73, 60
	s_cselect_b32 s27, s11, s25
	s_cselect_b32 s26, s10, s24
	s_cselect_b32 s25, s21, s72
	s_cselect_b32 s24, s20, s71
	s_sub_u32 s100, s4, 0x104000
	s_subb_u32 s101, s5, 0
	s_mov_b32 m0, s42
	s_nop 0
	global_load_lds_dwordx4 v152, s[100:101]
	s_mov_b32 m0, s43
	s_nop 0
	global_load_lds_dwordx4 v156, s[100:101]
	s_add_i32 m0, s36, 0xc000
	ds_read_b128 v[192:195], v177
	ds_read_b128 v[196:199], v250
	ds_read_b128 v[206:209], v177 offset:2048
	ds_read_b128 v[210:213], v250 offset:2048
	ds_read_b128 v[214:217], v177 offset:4096
	ds_read_b128 v[218:221], v250 offset:4096
	ds_read_b128 v[222:225], v177 offset:6144
	ds_read_b128 v[226:229], v250 offset:6144
	global_load_lds_dwordx4 v164, s[4:5]
	s_add_i32 m0, s36, 0xe000
	s_nop 0
	global_load_lds_dwordx4 v166, s[4:5]
	s_waitcnt vmcnt(8)
	s_waitcnt lgkmcnt(0)
	s_setprio 2
	s_barrier
	v_mfma_f32_16x16x32_bf16 v[128:131], v[112:115], v[192:195], v[128:131]
	v_mfma_f32_16x16x32_bf16 v[128:131], v[132:135], v[196:199], v[128:131]
	v_mfma_f32_16x16x32_bf16 v[124:127], v[136:139], v[192:195], v[124:127]
	v_mfma_f32_16x16x32_bf16 v[124:127], v[140:143], v[196:199], v[124:127]
	v_mfma_f32_16x16x32_bf16 v[108:111], v[112:115], v[206:209], v[108:111]
	v_mfma_f32_16x16x32_bf16 v[108:111], v[132:135], v[210:213], v[108:111]
	v_mfma_f32_16x16x32_bf16 v[104:107], v[136:139], v[206:209], v[104:107]
	v_mfma_f32_16x16x32_bf16 v[104:107], v[140:143], v[210:213], v[104:107]
	v_mfma_f32_16x16x32_bf16 v[92:95], v[112:115], v[214:217], v[92:95]
	v_mfma_f32_16x16x32_bf16 v[92:95], v[132:135], v[218:221], v[92:95]
	v_mfma_f32_16x16x32_bf16 v[88:91], v[136:139], v[214:217], v[88:91]
	v_mfma_f32_16x16x32_bf16 v[88:91], v[140:143], v[218:221], v[88:91]
	v_mfma_f32_16x16x32_bf16 v[76:79], v[112:115], v[222:225], v[76:79]
	v_mfma_f32_16x16x32_bf16 v[76:79], v[132:135], v[226:229], v[76:79]
	v_mfma_f32_16x16x32_bf16 v[72:75], v[136:139], v[222:225], v[72:75]
	v_mfma_f32_16x16x32_bf16 v[72:75], v[140:143], v[226:229], v[72:75]
	s_setprio 0
	s_setprio 2
	v_mfma_f32_16x16x32_bf16 v[120:123], v[144:147], v[192:195], v[120:123]
	v_mfma_f32_16x16x32_bf16 v[120:123], v[148:151], v[196:199], v[120:123]
	v_mfma_f32_16x16x32_bf16 v[116:119], v[184:187], v[192:195], v[116:119]
	v_mfma_f32_16x16x32_bf16 v[116:119], v[188:191], v[196:199], v[116:119]
	v_mfma_f32_16x16x32_bf16 v[100:103], v[144:147], v[206:209], v[100:103]
	v_mfma_f32_16x16x32_bf16 v[100:103], v[148:151], v[210:213], v[100:103]
	v_mfma_f32_16x16x32_bf16 v[96:99], v[184:187], v[206:209], v[96:99]
	v_mfma_f32_16x16x32_bf16 v[96:99], v[188:191], v[210:213], v[96:99]
	v_mfma_f32_16x16x32_bf16 v[84:87], v[144:147], v[214:217], v[84:87]
	v_mfma_f32_16x16x32_bf16 v[84:87], v[148:151], v[218:221], v[84:87]
	v_mfma_f32_16x16x32_bf16 v[80:83], v[184:187], v[214:217], v[80:83]
	v_mfma_f32_16x16x32_bf16 v[80:83], v[188:191], v[218:221], v[80:83]
	v_mfma_f32_16x16x32_bf16 v[68:71], v[144:147], v[222:225], v[68:71]
	v_mfma_f32_16x16x32_bf16 v[68:71], v[148:151], v[226:229], v[68:71]
	v_mfma_f32_16x16x32_bf16 v[64:67], v[184:187], v[222:225], v[64:67]
	s_setprio 3
	s_barrier
; #define PG8_STAGE(bufoff, gbase, voff) do { _Pragma("unroll") for (int _i = 0; _i < 2; ++_i) \
;         __builtin_amdgcn_global_load_lds((const unsigned*)((const char*)(gbase) + (voff)[_i]), (LAS unsigned*)(lds + (bufoff) + ldsw + _i * 8192), 16, 0, 0); } while (0)
; #define PG8_LDA(dst, b, h) do { _Pragma("unroll") for (int m = 0; m < 4; ++m) _Pragma("unroll") for (int k = 0; k < 2; ++k) dst[m][k] = *(const LAS bf16x8*)(lds + PG8_SA(b, h) + aoff + m * 2048 + k * 1024); } while (0)
; #define PG8_LDB(dst, b, h) do { _Pragma("unroll") for (int n = 0; n < 2; ++n) _Pragma("unroll") for (int k = 0; k < 2; ++k) dst[n][k] = *(const LAS bf16x8*)(lds + PG8_SB(b, h) + boff + n * 2048 + k * 1024); } while (0)
; #define PG8_MMA(ai, bj, At, Bt) do { __builtin_amdgcn_s_setprio(3); _Pragma("unroll") for (int m = 0; m < 4; ++m) _Pragma("unroll") for (int n = 0; n < 2; ++n) _Pragma("unroll") for (int k = 0; k < 2; ++k) \
;         acc[ai][bj][m][n] = __builtin_amdgcn_mfma_f32_16x16x32_bf16(Bt[n][k], At[m][k], acc[ai][bj][m][n], 0, 0, 0); __builtin_amdgcn_s_setprio(0); } while (0)
; #define PG8_WAIT_V(n) asm volatile("s_waitcnt vmcnt(" #n ")" ::: "memory")
; #define PG8_WAIT_L(n) asm volatile("s_waitcnt lgkmcnt(" #n ")" ::: "memory")
; #define PG8_BAR __builtin_amdgcn_s_barrier()
; #define PG8_SCHED __builtin_amdgcn_sched_barrier(0)
; template <class Epi, class Sched, bool ALIGN_EPI = false, bool SP2 = false>
; __device__ __forceinline__ void gemm_phase(LAS unsigned char* lds, const Gemm g, const Sched& S, const Epi& E) {
;     ...
;             PG8_WAIT_V(8); PG8_WAIT_L(0); PG8_BAR; PG8_MMA(0, 0, At, B0); PG8_MMA(0, 1, At, B1); PG8_BAR; PG8_SCHED;
;             PG8_LDA(At, 0, 1); PG8_STAGE(PG8_SB(0, 0), b2, voffB); PG8_STAGE(PG8_SB(0, 1), b2 + hsB, voffB); PG8_STAGE(PG8_SA(0, 0), a2, voffA);
;             PG8_WAIT_V(8); PG8_WAIT_L(0); PG8_BAR; PG8_MMA(1, 0, At, B0); PG8_MMA(1, 1, At, B1); PG8_BAR; PG8_SCHED;
;             PG8_LDB(B0, 1, 0); PG8_LDB(B1, 1, 1); PG8_SCHED; PG8_LDA(At, 1, 0); PG8_STAGE(PG8_SA(0, 1), a2 + hsA, voffA);
	v_mfma_f32_16x16x32_bf16 v[64:67], v[188:191], v[226:229], v[64:67]
	s_setprio 0
	s_add_i32 s74, s45, s31
	s_mov_b32 m0, s74
	ds_read_b128 v[192:195], v177 offset:16384
	ds_read_b128 v[196:199], v250 offset:16384
	ds_read_b128 v[206:209], v177 offset:18432
	ds_read_b128 v[210:213], v250 offset:18432
	ds_read_b128 v[214:217], v177 offset:20480
	ds_read_b128 v[218:221], v250 offset:20480
	ds_read_b128 v[222:225], v177 offset:22528
	ds_read_b128 v[226:229], v250 offset:22528
	global_load_lds_dwordx4 v154, s[24:25]
	s_add_i32 m0, s74, 0x2000
	s_add_u32 s74, s24, 0x41000
	s_addc_u32 s75, s25, 0
	s_add_i32 s78, s46, s31
	global_load_lds_dwordx4 v158, s[24:25]
	s_mov_b32 m0, s78
	s_nop 0
	global_load_lds_dwordx4 v154, s[74:75]
	s_add_i32 m0, s78, 0x2000
	s_nop 0
	global_load_lds_dwordx4 v158, s[74:75]
	s_waitcnt vmcnt(6)
	s_waitcnt lgkmcnt(0)
	s_setprio 2
	s_barrier
	v_mfma_f32_16x16x32_bf16 v[60:63], v[112:115], v[192:195], v[60:63]
	v_mfma_f32_16x16x32_bf16 v[60:63], v[132:135], v[196:199], v[60:63]
	v_mfma_f32_16x16x32_bf16 v[56:59], v[136:139], v[192:195], v[56:59]
	v_mfma_f32_16x16x32_bf16 v[56:59], v[140:143], v[196:199], v[56:59]
	v_mfma_f32_16x16x32_bf16 v[44:47], v[112:115], v[206:209], v[44:47]
	v_mfma_f32_16x16x32_bf16 v[44:47], v[132:135], v[210:213], v[44:47]
	v_mfma_f32_16x16x32_bf16 v[40:43], v[136:139], v[206:209], v[40:43]
	v_mfma_f32_16x16x32_bf16 v[40:43], v[140:143], v[210:213], v[40:43]
	v_mfma_f32_16x16x32_bf16 v[28:31], v[112:115], v[214:217], v[28:31]
	v_mfma_f32_16x16x32_bf16 v[28:31], v[132:135], v[218:221], v[28:31]
	v_mfma_f32_16x16x32_bf16 v[24:27], v[136:139], v[214:217], v[24:27]
	v_mfma_f32_16x16x32_bf16 v[24:27], v[140:143], v[218:221], v[24:27]
	v_mfma_f32_16x16x32_bf16 v[12:15], v[112:115], v[222:225], v[12:15]
	v_mfma_f32_16x16x32_bf16 v[12:15], v[132:135], v[226:229], v[12:15]
	v_mfma_f32_16x16x32_bf16 v[8:11], v[136:139], v[222:225], v[8:11]
	v_mfma_f32_16x16x32_bf16 v[8:11], v[140:143], v[226:229], v[8:11]
	s_setprio 0
	s_setprio 2
	v_mfma_f32_16x16x32_bf16 v[52:55], v[144:147], v[192:195], v[52:55]
	v_mfma_f32_16x16x32_bf16 v[52:55], v[148:151], v[196:199], v[52:55]
	v_mfma_f32_16x16x32_bf16 v[48:51], v[184:187], v[192:195], v[48:51]
	v_mfma_f32_16x16x32_bf16 v[48:51], v[188:191], v[196:199], v[48:51]
	v_mfma_f32_16x16x32_bf16 v[36:39], v[144:147], v[206:209], v[36:39]
	v_mfma_f32_16x16x32_bf16 v[36:39], v[148:151], v[210:213], v[36:39]
	v_mfma_f32_16x16x32_bf16 v[32:35], v[184:187], v[206:209], v[32:35]
	v_mfma_f32_16x16x32_bf16 v[32:35], v[188:191], v[210:213], v[32:35]
	v_mfma_f32_16x16x32_bf16 v[20:23], v[144:147], v[214:217], v[20:23]
	v_mfma_f32_16x16x32_bf16 v[20:23], v[148:151], v[218:221], v[20:23]
	v_mfma_f32_16x16x32_bf16 v[16:19], v[184:187], v[214:217], v[16:19]
	v_mfma_f32_16x16x32_bf16 v[16:19], v[188:191], v[218:221], v[16:19]
	v_mfma_f32_16x16x32_bf16 v[4:7], v[144:147], v[222:225], v[4:7]
	v_mfma_f32_16x16x32_bf16 v[4:7], v[148:151], v[226:229], v[4:7]
	v_mfma_f32_16x16x32_bf16 v[0:3], v[184:187], v[222:225], v[0:3]
	s_setprio 3
	s_barrier
	v_mfma_f32_16x16x32_bf16 v[0:3], v[188:191], v[226:229], v[0:3]
	s_setprio 0
	s_add_i32 s74, 0, 0x18000
	s_add_i32 s75, 0, 0x1c000
	ds_read_b128 v[112:115], v246
	ds_read_b128 v[132:135], v247
	ds_read_b128 v[136:139], v246 offset:2048
	ds_read_b128 v[140:143], v247 offset:2048
	ds_read_b128 v[144:147], v248
	ds_read_b128 v[148:151], v249
	ds_read_b128 v[184:187], v248 offset:2048
	ds_read_b128 v[188:191], v249 offset:2048
	s_mov_b32 m0, s36
	s_nop 0
	global_load_lds_dwordx4 v152, s[26:27]
	s_mov_b32 m0, s37
	s_nop 0
	global_load_lds_dwordx4 v156, s[26:27]
	s_add_u32 s26, s26, 0x104000
	s_addc_u32 s27, s27, 0
	s_mov_b32 m0, s38
	ds_read_b128 v[192:195], v177 offset:32768
	ds_read_b128 v[196:199], v250 offset:32768
	ds_read_b128 v[206:209], v177 offset:34816
	ds_read_b128 v[210:213], v250 offset:34816
	ds_read_b128 v[214:217], v177 offset:36864
	ds_read_b128 v[218:221], v250 offset:36864
	ds_read_b128 v[222:225], v177 offset:38912
	ds_read_b128 v[226:229], v250 offset:38912
	global_load_lds_dwordx4 v152, s[26:27]
	s_mov_b32 m0, s39
	s_nop 0
	global_load_lds_dwordx4 v156, s[26:27]
	s_waitcnt vmcnt(8)
	s_waitcnt lgkmcnt(0)
	s_setprio 2
	s_barrier
; #define PG8_STAGE(bufoff, gbase, voff) do { _Pragma("unroll") for (int _i = 0; _i < 2; ++_i) \
;         __builtin_amdgcn_global_load_lds((const unsigned*)((const char*)(gbase) + (voff)[_i]), (LAS unsigned*)(lds + (bufoff) + ldsw + _i * 8192), 16, 0, 0); } while (0)
; #define PG8_LDA(dst, b, h) do { _Pragma("unroll") for (int m = 0; m < 4; ++m) _Pragma("unroll") for (int k = 0; k < 2; ++k) dst[m][k] = *(const LAS bf16x8*)(lds + PG8_SA(b, h) + aoff + m * 2048 + k * 1024); } while (0)
; #define PG8_MMA(ai, bj, At, Bt) do { __builtin_amdgcn_s_setprio(3); _Pragma("unroll") for (int m = 0; m < 4; ++m) _Pragma("unroll") for (int n = 0; n < 2; ++n) _Pragma("unroll") for (int k = 0; k < 2; ++k) \
;         acc[ai][bj][m][n] = __builtin_amdgcn_mfma_f32_16x16x32_bf16(Bt[n][k], At[m][k], acc[ai][bj][m][n], 0, 0, 0); __builtin_amdgcn_s_setprio(0); } while (0)
; #define PG8_WAIT_V(n) asm volatile("s_waitcnt vmcnt(" #n ")" ::: "memory")
; #define PG8_WAIT_L(n) asm volatile("s_waitcnt lgkmcnt(" #n ")" ::: "memory")
; #define PG8_BAR __builtin_amdgcn_s_barrier()
; #define PG8_SCHED __builtin_amdgcn_sched_barrier(0)
; template <class Epi, class Sched, bool ALIGN_EPI = false, bool SP2 = false>
; __device__ __forceinline__ void gemm_phase(LAS unsigned char* lds, const Gemm g, const Sched& S, const Epi& E) {
;     ...
;             PG8_WAIT_V(8); PG8_WAIT_L(0); PG8_BAR; PG8_MMA(0, 0, At, B0); PG8_MMA(0, 1, At, B1); PG8_BAR; PG8_SCHED;
;             PG8_LDA(At, 1, 1); PG8_STAGE(PG8_SB(1, 0), b3, voffB); PG8_STAGE(PG8_SB(1, 1), b3 + hsB, voffB); PG8_STAGE(PG8_SA(1, 0), a3, voffA);
;             PG8_WAIT_V(8); PG8_WAIT_L(0); PG8_BAR; PG8_MMA(1, 0, At, B0); PG8_MMA(1, 1, At, B1); PG8_BAR; PG8_SCHED;
;     ...
;         if constexpr (ALIGN_EPI) { if (wr == 0) PG8_BAR; }
	v_mfma_f32_16x16x32_bf16 v[128:131], v[112:115], v[192:195], v[128:131]
	v_mfma_f32_16x16x32_bf16 v[128:131], v[132:135], v[196:199], v[128:131]
	v_mfma_f32_16x16x32_bf16 v[124:127], v[136:139], v[192:195], v[124:127]
	v_mfma_f32_16x16x32_bf16 v[124:127], v[140:143], v[196:199], v[124:127]
	v_mfma_f32_16x16x32_bf16 v[108:111], v[112:115], v[206:209], v[108:111]
	v_mfma_f32_16x16x32_bf16 v[108:111], v[132:135], v[210:213], v[108:111]
	v_mfma_f32_16x16x32_bf16 v[104:107], v[136:139], v[206:209], v[104:107]
	v_mfma_f32_16x16x32_bf16 v[104:107], v[140:143], v[210:213], v[104:107]
	v_mfma_f32_16x16x32_bf16 v[92:95], v[112:115], v[214:217], v[92:95]
	v_mfma_f32_16x16x32_bf16 v[92:95], v[132:135], v[218:221], v[92:95]
	v_mfma_f32_16x16x32_bf16 v[88:91], v[136:139], v[214:217], v[88:91]
	v_mfma_f32_16x16x32_bf16 v[88:91], v[140:143], v[218:221], v[88:91]
	v_mfma_f32_16x16x32_bf16 v[76:79], v[112:115], v[222:225], v[76:79]
	v_mfma_f32_16x16x32_bf16 v[76:79], v[132:135], v[226:229], v[76:79]
	v_mfma_f32_16x16x32_bf16 v[72:75], v[136:139], v[222:225], v[72:75]
	v_mfma_f32_16x16x32_bf16 v[72:75], v[140:143], v[226:229], v[72:75]
	s_setprio 0
	s_setprio 2
	v_mfma_f32_16x16x32_bf16 v[120:123], v[144:147], v[192:195], v[120:123]
	v_mfma_f32_16x16x32_bf16 v[120:123], v[148:151], v[196:199], v[120:123]
	v_mfma_f32_16x16x32_bf16 v[116:119], v[184:187], v[192:195], v[116:119]
	v_mfma_f32_16x16x32_bf16 v[116:119], v[188:191], v[196:199], v[116:119]
	v_mfma_f32_16x16x32_bf16 v[100:103], v[144:147], v[206:209], v[100:103]
	v_mfma_f32_16x16x32_bf16 v[100:103], v[148:151], v[210:213], v[100:103]
	v_mfma_f32_16x16x32_bf16 v[96:99], v[184:187], v[206:209], v[96:99]
	v_mfma_f32_16x16x32_bf16 v[96:99], v[188:191], v[210:213], v[96:99]
	v_mfma_f32_16x16x32_bf16 v[84:87], v[144:147], v[214:217], v[84:87]
	v_mfma_f32_16x16x32_bf16 v[84:87], v[148:151], v[218:221], v[84:87]
	v_mfma_f32_16x16x32_bf16 v[80:83], v[184:187], v[214:217], v[80:83]
	v_mfma_f32_16x16x32_bf16 v[80:83], v[188:191], v[218:221], v[80:83]
	v_mfma_f32_16x16x32_bf16 v[68:71], v[144:147], v[222:225], v[68:71]
	v_mfma_f32_16x16x32_bf16 v[68:71], v[148:151], v[226:229], v[68:71]
	v_mfma_f32_16x16x32_bf16 v[64:67], v[184:187], v[222:225], v[64:67]
	s_setprio 3
	s_barrier
	v_mfma_f32_16x16x32_bf16 v[64:67], v[188:191], v[226:229], v[64:67]
	s_setprio 0
	s_add_i32 s26, s74, s31
	s_add_u32 s100, s24, s14
	s_addc_u32 s101, s25, s15
	s_mov_b32 m0, s26
	ds_read_b128 v[192:195], v177 offset:49152
	ds_read_b128 v[196:199], v250 offset:49152
	ds_read_b128 v[206:209], v177 offset:51200
	ds_read_b128 v[210:213], v250 offset:51200
	ds_read_b128 v[214:217], v177 offset:53248
	ds_read_b128 v[218:221], v250 offset:53248
	ds_read_b128 v[222:225], v177 offset:55296
	ds_read_b128 v[226:229], v250 offset:55296
	global_load_lds_dwordx4 v154, s[100:101]
	s_add_i32 m0, s26, 0x2000
	s_add_u32 s24, s24, 0x41080
	s_addc_u32 s25, s25, 0
	s_add_i32 s26, s75, s31
	global_load_lds_dwordx4 v158, s[100:101]
	s_mov_b32 m0, s26
	s_nop 0
	global_load_lds_dwordx4 v154, s[24:25]
	s_add_i32 m0, s26, 0x2000
	s_nop 0
	global_load_lds_dwordx4 v158, s[24:25]
	s_waitcnt vmcnt(6)
	s_waitcnt lgkmcnt(0)
	s_setprio 2
	s_barrier
	v_mfma_f32_16x16x32_bf16 v[60:63], v[112:115], v[192:195], v[60:63]
	v_mfma_f32_16x16x32_bf16 v[60:63], v[132:135], v[196:199], v[60:63]
	v_mfma_f32_16x16x32_bf16 v[56:59], v[136:139], v[192:195], v[56:59]
	v_mfma_f32_16x16x32_bf16 v[56:59], v[140:143], v[196:199], v[56:59]
	v_mfma_f32_16x16x32_bf16 v[44:47], v[112:115], v[206:209], v[44:47]
	v_mfma_f32_16x16x32_bf16 v[44:47], v[132:135], v[210:213], v[44:47]
	v_mfma_f32_16x16x32_bf16 v[40:43], v[136:139], v[206:209], v[40:43]
	v_mfma_f32_16x16x32_bf16 v[40:43], v[140:143], v[210:213], v[40:43]
	v_mfma_f32_16x16x32_bf16 v[28:31], v[112:115], v[214:217], v[28:31]
	v_mfma_f32_16x16x32_bf16 v[28:31], v[132:135], v[218:221], v[28:31]
	v_mfma_f32_16x16x32_bf16 v[24:27], v[136:139], v[214:217], v[24:27]
	v_mfma_f32_16x16x32_bf16 v[24:27], v[140:143], v[218:221], v[24:27]
	v_mfma_f32_16x16x32_bf16 v[12:15], v[112:115], v[222:225], v[12:15]
	v_mfma_f32_16x16x32_bf16 v[12:15], v[132:135], v[226:229], v[12:15]
	v_mfma_f32_16x16x32_bf16 v[8:11], v[136:139], v[222:225], v[8:11]
	v_mfma_f32_16x16x32_bf16 v[8:11], v[140:143], v[226:229], v[8:11]
	s_setprio 0
	s_setprio 2
	v_mfma_f32_16x16x32_bf16 v[52:55], v[144:147], v[192:195], v[52:55]
	v_mfma_f32_16x16x32_bf16 v[52:55], v[148:151], v[196:199], v[52:55]
	v_mfma_f32_16x16x32_bf16 v[48:51], v[184:187], v[192:195], v[48:51]
	v_mfma_f32_16x16x32_bf16 v[48:51], v[188:191], v[196:199], v[48:51]
	v_mfma_f32_16x16x32_bf16 v[36:39], v[144:147], v[206:209], v[36:39]
	v_mfma_f32_16x16x32_bf16 v[36:39], v[148:151], v[210:213], v[36:39]
	v_mfma_f32_16x16x32_bf16 v[32:35], v[184:187], v[206:209], v[32:35]
	v_mfma_f32_16x16x32_bf16 v[32:35], v[188:191], v[210:213], v[32:35]
	v_mfma_f32_16x16x32_bf16 v[20:23], v[144:147], v[214:217], v[20:23]
	v_mfma_f32_16x16x32_bf16 v[20:23], v[148:151], v[218:221], v[20:23]
	v_mfma_f32_16x16x32_bf16 v[16:19], v[184:187], v[214:217], v[16:19]
	v_mfma_f32_16x16x32_bf16 v[16:19], v[188:191], v[218:221], v[16:19]
	v_mfma_f32_16x16x32_bf16 v[4:7], v[144:147], v[222:225], v[4:7]
	v_mfma_f32_16x16x32_bf16 v[4:7], v[148:151], v[226:229], v[4:7]
	v_mfma_f32_16x16x32_bf16 v[0:3], v[184:187], v[222:225], v[0:3]
	s_setprio 3
	s_barrier
	v_mfma_f32_16x16x32_bf16 v[0:3], v[188:191], v[226:229], v[0:3]
	s_setprio 0
	s_add_i32 s73, s73, 2
	s_add_u32 s4, s4, 0x100
	s_addc_u32 s5, s5, 0
	s_add_u32 s71, s71, 0x100
	s_addc_u32 s72, s72, 0
	s_cmp_gt_u32 s73, 61
	s_cbranch_scc0 .LBB0_309
	s_and_b64 vcc, exec, s[16:17]
	s_cbranch_vccz .LBB0_312
	s_barrier

; #define PG8_STAGE(bufoff, gbase, voff) do { _Pragma("unroll") for (int _i = 0; _i < 2; ++_i) \
;         __builtin_amdgcn_global_load_lds((const unsigned*)((const char*)(gbase) + (voff)[_i]), (LAS unsigned*)(lds + (bufoff) + ldsw + _i * 8192), 16, 0, 0); } while (0)
; #define PG8_LDA(dst, b, h) do { _Pragma("unroll") for (int m = 0; m < 4; ++m) _Pragma("unroll") for (int k = 0; k < 2; ++k) dst[m][k] = *(const LAS bf16x8*)(lds + PG8_SA(b, h) + aoff + m * 2048 + k * 1024); } while (0)
; #define PG8_LDB(dst, b, h) do { _Pragma("unroll") for (int n = 0; n < 2; ++n) _Pragma("unroll") for (int k = 0; k < 2; ++k) dst[n][k] = *(const LAS bf16x8*)(lds + PG8_SB(b, h) + boff + n * 2048 + k * 1024); } while (0)
; #define PG8_MMA(ai, bj, At, Bt) do { __builtin_amdgcn_s_setprio(3); _Pragma("unroll") for (int m = 0; m < 4; ++m) _Pragma("unroll") for (int n = 0; n < 2; ++n) _Pragma("unroll") for (int k = 0; k < 2; ++k) \
;         acc[ai][bj][m][n] = __builtin_amdgcn_mfma_f32_16x16x32_bf16(Bt[n][k], At[m][k], acc[ai][bj][m][n], 0, 0, 0); __builtin_amdgcn_s_setprio(0); } while (0)
; #define PG8_WAIT_V(n) asm volatile("s_waitcnt vmcnt(" #n ")" ::: "memory")
; #define PG8_WAIT_L(n) asm volatile("s_waitcnt lgkmcnt(" #n ")" ::: "memory")
; #define PG8_BAR __builtin_amdgcn_s_barrier()
; #define PG8_SCHED __builtin_amdgcn_sched_barrier(0)
; template <class Epi, class Sched, bool ALIGN_EPI = false, bool SP2 = false>
; __device__ __forceinline__ void gemm_phase(LAS unsigned char* lds, const Gemm g, const Sched& S, const Epi& E) {
;     ...
;             PG8_LDB(B0, 0, 0); PG8_LDB(B1, 0, 1); PG8_SCHED; PG8_LDA(At, 0, 0); PG8_STAGE(PG8_SA(1, 1), a1 + hsA, voffA);
;             PG8_WAIT_V(8); PG8_WAIT_L(0); PG8_BAR; PG8_MMA(0, 0, At, B0); PG8_MMA(0, 1, At, B1); PG8_BAR; PG8_SCHED;
;     ...
; #pragma unroll
;         for (int a = 0; a < 2; ++a)
; #pragma unroll
;             for (int b = 0; b < 2; ++b)
; #pragma unroll
;                 for (int m = 0; m < 4; ++m)
; #pragma unroll
;                     for (int n = 0; n < 2; ++n) acc[a][b][m][n] = (f32x4){0.f, 0.f, 0.f, 0.f};
;         cur = nxt; cA = nA; cB = nB; ++ui;
.LBB0_349:
	s_add_u32 s14, s14, 0x404080
	s_addc_u32 s15, s15, 0
	s_add_u32 s48, s16, 0x100
	v_mov_b32_e32 v0, 0
	s_addc_u32 s49, s17, 0
	s_mov_b32 s50, -2
	v_mov_b32_e32 v1, v0
	v_mov_b32_e32 v2, v0
	v_mov_b32_e32 v3, v0
	v_mov_b32_e32 v4, v0
	v_mov_b32_e32 v5, v0
	v_mov_b32_e32 v6, v0
	v_mov_b32_e32 v7, v0
	v_mov_b32_e32 v16, v0
	v_mov_b32_e32 v17, v0
	v_mov_b32_e32 v18, v0
	v_mov_b32_e32 v19, v0
	v_mov_b32_e32 v20, v0
	v_mov_b32_e32 v21, v0
	v_mov_b32_e32 v22, v0
	v_mov_b32_e32 v23, v0
	v_mov_b32_e32 v32, v0
	v_mov_b32_e32 v33, v0
	v_mov_b32_e32 v34, v0
	v_mov_b32_e32 v35, v0
	v_mov_b32_e32 v36, v0
	v_mov_b32_e32 v37, v0
	v_mov_b32_e32 v38, v0
	v_mov_b32_e32 v39, v0
	v_mov_b32_e32 v48, v0
	v_mov_b32_e32 v49, v0
	v_mov_b32_e32 v50, v0
	v_mov_b32_e32 v51, v0
	v_mov_b32_e32 v52, v0
	v_mov_b32_e32 v53, v0
	v_mov_b32_e32 v54, v0
	v_mov_b32_e32 v55, v0
	v_mov_b32_e32 v8, v0
	v_mov_b32_e32 v9, v0
	v_mov_b32_e32 v10, v0
	v_mov_b32_e32 v11, v0
	v_mov_b32_e32 v12, v0
	v_mov_b32_e32 v13, v0
	v_mov_b32_e32 v14, v0
	v_mov_b32_e32 v15, v0
	v_mov_b32_e32 v24, v0
	v_mov_b32_e32 v25, v0
	v_mov_b32_e32 v26, v0
	v_mov_b32_e32 v27, v0
	v_mov_b32_e32 v28, v0
	v_mov_b32_e32 v29, v0
	v_mov_b32_e32 v30, v0
	v_mov_b32_e32 v31, v0
	v_mov_b32_e32 v40, v0
	v_mov_b32_e32 v41, v0
	v_mov_b32_e32 v42, v0
	v_mov_b32_e32 v43, v0
	v_mov_b32_e32 v44, v0
	v_mov_b32_e32 v45, v0
	v_mov_b32_e32 v46, v0
	v_mov_b32_e32 v47, v0
	v_mov_b32_e32 v56, v0
	v_mov_b32_e32 v57, v0
	v_mov_b32_e32 v58, v0
	v_mov_b32_e32 v59, v0
	v_mov_b32_e32 v60, v0
	v_mov_b32_e32 v61, v0
	v_mov_b32_e32 v62, v0
	v_mov_b32_e32 v63, v0
	v_mov_b32_e32 v64, v0
	v_mov_b32_e32 v65, v0
	v_mov_b32_e32 v66, v0
	v_mov_b32_e32 v67, v0
	v_mov_b32_e32 v68, v0
	v_mov_b32_e32 v69, v0
	v_mov_b32_e32 v70, v0
	v_mov_b32_e32 v71, v0
	v_mov_b32_e32 v80, v0
	v_mov_b32_e32 v81, v0
	v_mov_b32_e32 v82, v0
	v_mov_b32_e32 v83, v0
	v_mov_b32_e32 v84, v0
	v_mov_b32_e32 v85, v0
	v_mov_b32_e32 v86, v0
	v_mov_b32_e32 v87, v0
	v_mov_b32_e32 v96, v0
	v_mov_b32_e32 v97, v0
	v_mov_b32_e32 v98, v0
	v_mov_b32_e32 v99, v0
	v_mov_b32_e32 v100, v0
	v_mov_b32_e32 v101, v0
	v_mov_b32_e32 v102, v0
	v_mov_b32_e32 v103, v0
	v_mov_b32_e32 v112, v0
	v_mov_b32_e32 v113, v0
	v_mov_b32_e32 v114, v0
	v_mov_b32_e32 v115, v0
	v_mov_b32_e32 v116, v0
	v_mov_b32_e32 v117, v0
	v_mov_b32_e32 v118, v0
	v_mov_b32_e32 v119, v0
	v_mov_b32_e32 v72, v0
	v_mov_b32_e32 v73, v0
	v_mov_b32_e32 v74, v0
	v_mov_b32_e32 v75, v0
	v_mov_b32_e32 v76, v0
	v_mov_b32_e32 v77, v0
	v_mov_b32_e32 v78, v0
	v_mov_b32_e32 v79, v0
	v_mov_b32_e32 v88, v0
	v_mov_b32_e32 v89, v0
	v_mov_b32_e32 v90, v0
	v_mov_b32_e32 v91, v0
	v_mov_b32_e32 v92, v0
	v_mov_b32_e32 v93, v0
	v_mov_b32_e32 v94, v0
	v_mov_b32_e32 v95, v0
	v_mov_b32_e32 v104, v0
	v_mov_b32_e32 v105, v0
	v_mov_b32_e32 v106, v0
	v_mov_b32_e32 v107, v0
	v_mov_b32_e32 v108, v0
	v_mov_b32_e32 v109, v0
	v_mov_b32_e32 v110, v0
	v_mov_b32_e32 v111, v0
	v_mov_b32_e32 v120, v0
	v_mov_b32_e32 v121, v0
	v_mov_b32_e32 v122, v0
	v_mov_b32_e32 v123, v0
	v_mov_b32_e32 v124, v0
	v_mov_b32_e32 v125, v0
	v_mov_b32_e32 v126, v0
	v_mov_b32_e32 v127, v0
	v_add_u32_e32 v246, 0x18000, v146
	v_xor_b32_e32 v247, 64, v246
	v_add_u32_e32 v248, 0x1c000, v146
	v_xor_b32_e32 v249, 64, v248
.LBB0_350:
	ds_read_b128 v[140:143], v149
	ds_read_b128 v[156:159], v251
	ds_read_b128 v[160:163], v149 offset:2048
	ds_read_b128 v[164:167], v251 offset:2048
	ds_read_b128 v[168:171], v150
	ds_read_b128 v[172:175], v252
	ds_read_b128 v[176:179], v150 offset:2048
	ds_read_b128 v[180:183], v252 offset:2048
	s_add_u32 s16, s14, 0xffbfc080
	s_addc_u32 s17, s15, -1
	s_cmpk_eq_i32 s50, 0xfc
	s_cselect_b32 s21, s5, s17
	s_cselect_b32 s20, s4, s16
	s_cselect_b32 s17, s13, s49
	s_cselect_b32 s16, s12, s48
	s_sub_u32 s100, s14, 0x404000
	s_subb_u32 s101, s15, 0
	s_mov_b32 m0, s33
	s_nop 0
	global_load_lds_dwordx4 v128, s[100:101]
	s_mov_b32 m0, s38
	s_nop 0
	global_load_lds_dwordx4 v130, s[100:101]
	s_add_i32 m0, s26, 0xc000
	ds_read_b128 v[184:187], v151
	ds_read_b128 v[188:191], v250
	ds_read_b128 v[192:195], v151 offset:2048
	ds_read_b128 v[196:199], v250 offset:2048
	ds_read_b128 v[200:203], v151 offset:4096
	ds_read_b128 v[204:207], v250 offset:4096
	ds_read_b128 v[208:211], v151 offset:6144
	ds_read_b128 v[212:215], v250 offset:6144
	global_load_lds_dwordx4 v132, s[14:15]
	s_add_i32 m0, s26, 0xe000
	s_nop 0
	global_load_lds_dwordx4 v134, s[14:15]
	s_waitcnt vmcnt(8)
	s_waitcnt lgkmcnt(0)
	s_setprio 2
	s_barrier
	v_mfma_f32_16x16x32_bf16 v[124:127], v[140:143], v[184:187], v[124:127]
	v_mfma_f32_16x16x32_bf16 v[124:127], v[156:159], v[188:191], v[124:127]
	v_mfma_f32_16x16x32_bf16 v[120:123], v[160:163], v[184:187], v[120:123]
	v_mfma_f32_16x16x32_bf16 v[120:123], v[164:167], v[188:191], v[120:123]
	v_mfma_f32_16x16x32_bf16 v[108:111], v[140:143], v[192:195], v[108:111]
	v_mfma_f32_16x16x32_bf16 v[108:111], v[156:159], v[196:199], v[108:111]
	v_mfma_f32_16x16x32_bf16 v[104:107], v[160:163], v[192:195], v[104:107]
	v_mfma_f32_16x16x32_bf16 v[104:107], v[164:167], v[196:199], v[104:107]
	v_mfma_f32_16x16x32_bf16 v[92:95], v[140:143], v[200:203], v[92:95]
	v_mfma_f32_16x16x32_bf16 v[92:95], v[156:159], v[204:207], v[92:95]
	v_mfma_f32_16x16x32_bf16 v[88:91], v[160:163], v[200:203], v[88:91]
	v_mfma_f32_16x16x32_bf16 v[88:91], v[164:167], v[204:207], v[88:91]
	v_mfma_f32_16x16x32_bf16 v[76:79], v[140:143], v[208:211], v[76:79]
	v_mfma_f32_16x16x32_bf16 v[76:79], v[156:159], v[212:215], v[76:79]
	v_mfma_f32_16x16x32_bf16 v[72:75], v[160:163], v[208:211], v[72:75]
	v_mfma_f32_16x16x32_bf16 v[72:75], v[164:167], v[212:215], v[72:75]
	s_setprio 0
	s_setprio 2
	v_mfma_f32_16x16x32_bf16 v[116:119], v[168:171], v[184:187], v[116:119]
	v_mfma_f32_16x16x32_bf16 v[116:119], v[172:175], v[188:191], v[116:119]
	v_mfma_f32_16x16x32_bf16 v[112:115], v[176:179], v[184:187], v[112:115]
	v_mfma_f32_16x16x32_bf16 v[112:115], v[180:183], v[188:191], v[112:115]
	v_mfma_f32_16x16x32_bf16 v[100:103], v[168:171], v[192:195], v[100:103]
	v_mfma_f32_16x16x32_bf16 v[100:103], v[172:175], v[196:199], v[100:103]
	v_mfma_f32_16x16x32_bf16 v[96:99], v[176:179], v[192:195], v[96:99]
	v_mfma_f32_16x16x32_bf16 v[96:99], v[180:183], v[196:199], v[96:99]
	v_mfma_f32_16x16x32_bf16 v[84:87], v[168:171], v[200:203], v[84:87]
	v_mfma_f32_16x16x32_bf16 v[84:87], v[172:175], v[204:207], v[84:87]
	v_mfma_f32_16x16x32_bf16 v[80:83], v[176:179], v[200:203], v[80:83]
	v_mfma_f32_16x16x32_bf16 v[80:83], v[180:183], v[204:207], v[80:83]
	v_mfma_f32_16x16x32_bf16 v[68:71], v[168:171], v[208:211], v[68:71]
	v_mfma_f32_16x16x32_bf16 v[68:71], v[172:175], v[212:215], v[68:71]
	s_setprio 3
	s_barrier
; #define PG8_STAGE(bufoff, gbase, voff) do { _Pragma("unroll") for (int _i = 0; _i < 2; ++_i) \
;         __builtin_amdgcn_global_load_lds((const unsigned*)((const char*)(gbase) + (voff)[_i]), (LAS unsigned*)(lds + (bufoff) + ldsw + _i * 8192), 16, 0, 0); } while (0)
; #define PG8_LDA(dst, b, h) do { _Pragma("unroll") for (int m = 0; m < 4; ++m) _Pragma("unroll") for (int k = 0; k < 2; ++k) dst[m][k] = *(const LAS bf16x8*)(lds + PG8_SA(b, h) + aoff + m * 2048 + k * 1024); } while (0)
; #define PG8_LDB(dst, b, h) do { _Pragma("unroll") for (int n = 0; n < 2; ++n) _Pragma("unroll") for (int k = 0; k < 2; ++k) dst[n][k] = *(const LAS bf16x8*)(lds + PG8_SB(b, h) + boff + n * 2048 + k * 1024); } while (0)
; #define PG8_MMA(ai, bj, At, Bt) do { __builtin_amdgcn_s_setprio(3); _Pragma("unroll") for (int m = 0; m < 4; ++m) _Pragma("unroll") for (int n = 0; n < 2; ++n) _Pragma("unroll") for (int k = 0; k < 2; ++k) \
;         acc[ai][bj][m][n] = __builtin_amdgcn_mfma_f32_16x16x32_bf16(Bt[n][k], At[m][k], acc[ai][bj][m][n], 0, 0, 0); __builtin_amdgcn_s_setprio(0); } while (0)
; #define PG8_WAIT_V(n) asm volatile("s_waitcnt vmcnt(" #n ")" ::: "memory")
; #define PG8_WAIT_L(n) asm volatile("s_waitcnt lgkmcnt(" #n ")" ::: "memory")
; #define PG8_BAR __builtin_amdgcn_s_barrier()
; #define PG8_SCHED __builtin_amdgcn_sched_barrier(0)
; template <class Epi, class Sched, bool ALIGN_EPI = false, bool SP2 = false>
; __device__ __forceinline__ void gemm_phase(LAS unsigned char* lds, const Gemm g, const Sched& S, const Epi& E) {
;     ...
;             PG8_WAIT_V(8); PG8_WAIT_L(0); PG8_BAR; PG8_MMA(0, 0, At, B0); PG8_MMA(0, 1, At, B1); PG8_BAR; PG8_SCHED;
;             PG8_LDA(At, 0, 1); PG8_STAGE(PG8_SB(0, 0), b2, voffB); PG8_STAGE(PG8_SB(0, 1), b2 + hsB, voffB); PG8_STAGE(PG8_SA(0, 0), a2, voffA);
;             PG8_WAIT_V(8); PG8_WAIT_L(0); PG8_BAR; PG8_MMA(1, 0, At, B0); PG8_MMA(1, 1, At, B1); PG8_BAR; PG8_SCHED;
;             PG8_LDB(B0, 1, 0); PG8_LDB(B1, 1, 1); PG8_SCHED; PG8_LDA(At, 1, 0); PG8_STAGE(PG8_SA(0, 1), a2 + hsA, voffA);
;             PG8_WAIT_V(8); PG8_WAIT_L(0); PG8_BAR; PG8_MMA(0, 0, At, B0); PG8_MMA(0, 1, At, B1); PG8_BAR; PG8_SCHED;
	v_mfma_f32_16x16x32_bf16 v[64:67], v[176:179], v[208:211], v[64:67]
	v_mfma_f32_16x16x32_bf16 v[64:67], v[180:183], v[212:215], v[64:67]
	s_setprio 0
	s_add_i32 s51, s41, s25
	s_mov_b32 m0, s51
	ds_read_b128 v[184:187], v151 offset:16384
	ds_read_b128 v[188:191], v250 offset:16384
	ds_read_b128 v[192:195], v151 offset:18432
	ds_read_b128 v[196:199], v250 offset:18432
	ds_read_b128 v[200:203], v151 offset:20480
	ds_read_b128 v[204:207], v250 offset:20480
	ds_read_b128 v[208:211], v151 offset:22528
	ds_read_b128 v[212:215], v250 offset:22528
	global_load_lds_dwordx4 v128, s[16:17]
	s_add_i32 m0, s51, 0x2000
	s_add_u32 s52, s16, 0x404000
	s_addc_u32 s53, s17, 0
	s_add_i32 s51, s42, s25
	global_load_lds_dwordx4 v130, s[16:17]
	s_mov_b32 m0, s51
	s_nop 0
	global_load_lds_dwordx4 v128, s[52:53]
	s_add_i32 m0, s51, 0x2000
	s_nop 0
	global_load_lds_dwordx4 v130, s[52:53]
	s_waitcnt vmcnt(6)
	s_waitcnt lgkmcnt(0)
	s_setprio 2
	s_barrier
	v_mfma_f32_16x16x32_bf16 v[60:63], v[140:143], v[184:187], v[60:63]
	v_mfma_f32_16x16x32_bf16 v[60:63], v[156:159], v[188:191], v[60:63]
	v_mfma_f32_16x16x32_bf16 v[56:59], v[160:163], v[184:187], v[56:59]
	v_mfma_f32_16x16x32_bf16 v[56:59], v[164:167], v[188:191], v[56:59]
	v_mfma_f32_16x16x32_bf16 v[44:47], v[140:143], v[192:195], v[44:47]
	v_mfma_f32_16x16x32_bf16 v[44:47], v[156:159], v[196:199], v[44:47]
	v_mfma_f32_16x16x32_bf16 v[40:43], v[160:163], v[192:195], v[40:43]
	v_mfma_f32_16x16x32_bf16 v[40:43], v[164:167], v[196:199], v[40:43]
	v_mfma_f32_16x16x32_bf16 v[28:31], v[140:143], v[200:203], v[28:31]
	v_mfma_f32_16x16x32_bf16 v[28:31], v[156:159], v[204:207], v[28:31]
	v_mfma_f32_16x16x32_bf16 v[24:27], v[160:163], v[200:203], v[24:27]
	v_mfma_f32_16x16x32_bf16 v[24:27], v[164:167], v[204:207], v[24:27]
	v_mfma_f32_16x16x32_bf16 v[12:15], v[140:143], v[208:211], v[12:15]
	v_mfma_f32_16x16x32_bf16 v[12:15], v[156:159], v[212:215], v[12:15]
	v_mfma_f32_16x16x32_bf16 v[8:11], v[160:163], v[208:211], v[8:11]
	v_mfma_f32_16x16x32_bf16 v[8:11], v[164:167], v[212:215], v[8:11]
	s_setprio 0
	s_setprio 2
	v_mfma_f32_16x16x32_bf16 v[52:55], v[168:171], v[184:187], v[52:55]
	v_mfma_f32_16x16x32_bf16 v[52:55], v[172:175], v[188:191], v[52:55]
	v_mfma_f32_16x16x32_bf16 v[48:51], v[176:179], v[184:187], v[48:51]
	v_mfma_f32_16x16x32_bf16 v[48:51], v[180:183], v[188:191], v[48:51]
	v_mfma_f32_16x16x32_bf16 v[36:39], v[168:171], v[192:195], v[36:39]
	v_mfma_f32_16x16x32_bf16 v[36:39], v[172:175], v[196:199], v[36:39]
	v_mfma_f32_16x16x32_bf16 v[32:35], v[176:179], v[192:195], v[32:35]
	v_mfma_f32_16x16x32_bf16 v[32:35], v[180:183], v[196:199], v[32:35]
	v_mfma_f32_16x16x32_bf16 v[20:23], v[168:171], v[200:203], v[20:23]
	v_mfma_f32_16x16x32_bf16 v[20:23], v[172:175], v[204:207], v[20:23]
	v_mfma_f32_16x16x32_bf16 v[16:19], v[176:179], v[200:203], v[16:19]
	v_mfma_f32_16x16x32_bf16 v[16:19], v[180:183], v[204:207], v[16:19]
	v_mfma_f32_16x16x32_bf16 v[4:7], v[168:171], v[208:211], v[4:7]
	v_mfma_f32_16x16x32_bf16 v[4:7], v[172:175], v[212:215], v[4:7]
	s_setprio 3
	s_barrier
	v_mfma_f32_16x16x32_bf16 v[0:3], v[176:179], v[208:211], v[0:3]
	v_mfma_f32_16x16x32_bf16 v[0:3], v[180:183], v[212:215], v[0:3]
	s_setprio 0
	s_add_i32 s51, 0, 0x18000
	s_add_i32 s52, 0, 0x1c000
	ds_read_b128 v[140:143], v246
	ds_read_b128 v[156:159], v247
	ds_read_b128 v[160:163], v246 offset:2048
	ds_read_b128 v[164:167], v247 offset:2048
	ds_read_b128 v[168:171], v248
	ds_read_b128 v[172:175], v249
	ds_read_b128 v[176:179], v248 offset:2048
	ds_read_b128 v[180:183], v249 offset:2048
	s_mov_b32 m0, s26
	s_nop 0
	global_load_lds_dwordx4 v128, s[20:21]
	s_mov_b32 m0, s27
	s_nop 0
	global_load_lds_dwordx4 v130, s[20:21]
	s_add_u32 s20, s20, 0x404000
	s_addc_u32 s21, s21, 0
	s_mov_b32 m0, s30
	ds_read_b128 v[184:187], v151 offset:32768
	ds_read_b128 v[188:191], v250 offset:32768
	ds_read_b128 v[192:195], v151 offset:34816
	ds_read_b128 v[196:199], v250 offset:34816
	ds_read_b128 v[200:203], v151 offset:36864
	ds_read_b128 v[204:207], v250 offset:36864
	ds_read_b128 v[208:211], v151 offset:38912
	ds_read_b128 v[212:215], v250 offset:38912
	global_load_lds_dwordx4 v128, s[20:21]
	s_mov_b32 m0, s31
	s_nop 0
	global_load_lds_dwordx4 v130, s[20:21]
	s_waitcnt vmcnt(8)
	s_waitcnt lgkmcnt(0)
	s_setprio 2
	s_barrier
; #define PG8_STAGE(bufoff, gbase, voff) do { _Pragma("unroll") for (int _i = 0; _i < 2; ++_i) \
;         __builtin_amdgcn_global_load_lds((const unsigned*)((const char*)(gbase) + (voff)[_i]), (LAS unsigned*)(lds + (bufoff) + ldsw + _i * 8192), 16, 0, 0); } while (0)
; #define PG8_LDA(dst, b, h) do { _Pragma("unroll") for (int m = 0; m < 4; ++m) _Pragma("unroll") for (int k = 0; k < 2; ++k) dst[m][k] = *(const LAS bf16x8*)(lds + PG8_SA(b, h) + aoff + m * 2048 + k * 1024); } while (0)
; #define PG8_MMA(ai, bj, At, Bt) do { __builtin_amdgcn_s_setprio(3); _Pragma("unroll") for (int m = 0; m < 4; ++m) _Pragma("unroll") for (int n = 0; n < 2; ++n) _Pragma("unroll") for (int k = 0; k < 2; ++k) \
;         acc[ai][bj][m][n] = __builtin_amdgcn_mfma_f32_16x16x32_bf16(Bt[n][k], At[m][k], acc[ai][bj][m][n], 0, 0, 0); __builtin_amdgcn_s_setprio(0); } while (0)
; #define PG8_WAIT_V(n) asm volatile("s_waitcnt vmcnt(" #n ")" ::: "memory")
; #define PG8_WAIT_L(n) asm volatile("s_waitcnt lgkmcnt(" #n ")" ::: "memory")
; #define PG8_BAR __builtin_amdgcn_s_barrier()
; #define PG8_SCHED __builtin_amdgcn_sched_barrier(0)
; template <class Epi, class Sched, bool ALIGN_EPI = false, bool SP2 = false>
; __device__ __forceinline__ void gemm_phase(LAS unsigned char* lds, const Gemm g, const Sched& S, const Epi& E) {
;     ...
;             PG8_WAIT_V(8); PG8_WAIT_L(0); PG8_BAR; PG8_MMA(0, 0, At, B0); PG8_MMA(0, 1, At, B1); PG8_BAR; PG8_SCHED;
;             PG8_LDA(At, 1, 1); PG8_STAGE(PG8_SB(1, 0), b3, voffB); PG8_STAGE(PG8_SB(1, 1), b3 + hsB, voffB); PG8_STAGE(PG8_SA(1, 0), a3, voffA);
;             PG8_WAIT_V(8); PG8_WAIT_L(0); PG8_BAR; PG8_MMA(1, 0, At, B0); PG8_MMA(1, 1, At, B1); PG8_BAR; PG8_SCHED;
;     ...
;         if constexpr (ALIGN_EPI) { if (wr == 0) PG8_BAR; }
	v_mfma_f32_16x16x32_bf16 v[124:127], v[140:143], v[184:187], v[124:127]
	v_mfma_f32_16x16x32_bf16 v[124:127], v[156:159], v[188:191], v[124:127]
	v_mfma_f32_16x16x32_bf16 v[120:123], v[160:163], v[184:187], v[120:123]
	v_mfma_f32_16x16x32_bf16 v[120:123], v[164:167], v[188:191], v[120:123]
	v_mfma_f32_16x16x32_bf16 v[108:111], v[140:143], v[192:195], v[108:111]
	v_mfma_f32_16x16x32_bf16 v[108:111], v[156:159], v[196:199], v[108:111]
	v_mfma_f32_16x16x32_bf16 v[104:107], v[160:163], v[192:195], v[104:107]
	v_mfma_f32_16x16x32_bf16 v[104:107], v[164:167], v[196:199], v[104:107]
	v_mfma_f32_16x16x32_bf16 v[92:95], v[140:143], v[200:203], v[92:95]
	v_mfma_f32_16x16x32_bf16 v[92:95], v[156:159], v[204:207], v[92:95]
	v_mfma_f32_16x16x32_bf16 v[88:91], v[160:163], v[200:203], v[88:91]
	v_mfma_f32_16x16x32_bf16 v[88:91], v[164:167], v[204:207], v[88:91]
	v_mfma_f32_16x16x32_bf16 v[76:79], v[140:143], v[208:211], v[76:79]
	v_mfma_f32_16x16x32_bf16 v[76:79], v[156:159], v[212:215], v[76:79]
	v_mfma_f32_16x16x32_bf16 v[72:75], v[160:163], v[208:211], v[72:75]
	v_mfma_f32_16x16x32_bf16 v[72:75], v[164:167], v[212:215], v[72:75]
	s_setprio 0
	s_setprio 2
	v_mfma_f32_16x16x32_bf16 v[116:119], v[168:171], v[184:187], v[116:119]
	v_mfma_f32_16x16x32_bf16 v[116:119], v[172:175], v[188:191], v[116:119]
	v_mfma_f32_16x16x32_bf16 v[112:115], v[176:179], v[184:187], v[112:115]
	v_mfma_f32_16x16x32_bf16 v[112:115], v[180:183], v[188:191], v[112:115]
	v_mfma_f32_16x16x32_bf16 v[100:103], v[168:171], v[192:195], v[100:103]
	v_mfma_f32_16x16x32_bf16 v[100:103], v[172:175], v[196:199], v[100:103]
	v_mfma_f32_16x16x32_bf16 v[96:99], v[176:179], v[192:195], v[96:99]
	v_mfma_f32_16x16x32_bf16 v[96:99], v[180:183], v[196:199], v[96:99]
	v_mfma_f32_16x16x32_bf16 v[84:87], v[168:171], v[200:203], v[84:87]
	v_mfma_f32_16x16x32_bf16 v[84:87], v[172:175], v[204:207], v[84:87]
	v_mfma_f32_16x16x32_bf16 v[80:83], v[176:179], v[200:203], v[80:83]
	v_mfma_f32_16x16x32_bf16 v[80:83], v[180:183], v[204:207], v[80:83]
	v_mfma_f32_16x16x32_bf16 v[68:71], v[168:171], v[208:211], v[68:71]
	v_mfma_f32_16x16x32_bf16 v[68:71], v[172:175], v[212:215], v[68:71]
	s_setprio 3
	s_barrier
	v_mfma_f32_16x16x32_bf16 v[64:67], v[176:179], v[208:211], v[64:67]
	v_mfma_f32_16x16x32_bf16 v[64:67], v[180:183], v[212:215], v[64:67]
	s_setprio 0
	s_add_i32 s20, s51, s25
	s_add_u32 s100, s16, s8
	s_addc_u32 s101, s17, s9
	s_mov_b32 m0, s20
	ds_read_b128 v[184:187], v151 offset:49152
	ds_read_b128 v[188:191], v250 offset:49152
	ds_read_b128 v[192:195], v151 offset:51200
	ds_read_b128 v[196:199], v250 offset:51200
	ds_read_b128 v[200:203], v151 offset:53248
	ds_read_b128 v[204:207], v250 offset:53248
	ds_read_b128 v[208:211], v151 offset:55296
	ds_read_b128 v[212:215], v250 offset:55296
	global_load_lds_dwordx4 v128, s[100:101]
	s_add_i32 m0, s20, 0x2000
	s_add_u32 s16, s16, 0x404080
	s_addc_u32 s17, s17, 0
	s_add_i32 s20, s52, s25
	global_load_lds_dwordx4 v130, s[100:101]
	s_mov_b32 m0, s20
	s_nop 0
	global_load_lds_dwordx4 v128, s[16:17]
	s_add_i32 m0, s20, 0x2000
	s_nop 0
	global_load_lds_dwordx4 v130, s[16:17]
	s_waitcnt vmcnt(6)
	s_waitcnt lgkmcnt(0)
	s_setprio 2
	s_barrier
	v_mfma_f32_16x16x32_bf16 v[60:63], v[140:143], v[184:187], v[60:63]
	v_mfma_f32_16x16x32_bf16 v[60:63], v[156:159], v[188:191], v[60:63]
	v_mfma_f32_16x16x32_bf16 v[56:59], v[160:163], v[184:187], v[56:59]
	v_mfma_f32_16x16x32_bf16 v[56:59], v[164:167], v[188:191], v[56:59]
	v_mfma_f32_16x16x32_bf16 v[44:47], v[140:143], v[192:195], v[44:47]
	v_mfma_f32_16x16x32_bf16 v[44:47], v[156:159], v[196:199], v[44:47]
	v_mfma_f32_16x16x32_bf16 v[40:43], v[160:163], v[192:195], v[40:43]
	v_mfma_f32_16x16x32_bf16 v[40:43], v[164:167], v[196:199], v[40:43]
	v_mfma_f32_16x16x32_bf16 v[28:31], v[140:143], v[200:203], v[28:31]
	v_mfma_f32_16x16x32_bf16 v[28:31], v[156:159], v[204:207], v[28:31]
	v_mfma_f32_16x16x32_bf16 v[24:27], v[160:163], v[200:203], v[24:27]
	v_mfma_f32_16x16x32_bf16 v[24:27], v[164:167], v[204:207], v[24:27]
	v_mfma_f32_16x16x32_bf16 v[12:15], v[140:143], v[208:211], v[12:15]
	v_mfma_f32_16x16x32_bf16 v[12:15], v[156:159], v[212:215], v[12:15]
	v_mfma_f32_16x16x32_bf16 v[8:11], v[160:163], v[208:211], v[8:11]
	v_mfma_f32_16x16x32_bf16 v[8:11], v[164:167], v[212:215], v[8:11]
	s_setprio 0
	s_setprio 2
	v_mfma_f32_16x16x32_bf16 v[52:55], v[168:171], v[184:187], v[52:55]
	v_mfma_f32_16x16x32_bf16 v[52:55], v[172:175], v[188:191], v[52:55]
	v_mfma_f32_16x16x32_bf16 v[48:51], v[176:179], v[184:187], v[48:51]
	v_mfma_f32_16x16x32_bf16 v[48:51], v[180:183], v[188:191], v[48:51]
	v_mfma_f32_16x16x32_bf16 v[36:39], v[168:171], v[192:195], v[36:39]
	v_mfma_f32_16x16x32_bf16 v[36:39], v[172:175], v[196:199], v[36:39]
	v_mfma_f32_16x16x32_bf16 v[32:35], v[176:179], v[192:195], v[32:35]
	v_mfma_f32_16x16x32_bf16 v[32:35], v[180:183], v[196:199], v[32:35]
	v_mfma_f32_16x16x32_bf16 v[20:23], v[168:171], v[200:203], v[20:23]
	v_mfma_f32_16x16x32_bf16 v[20:23], v[172:175], v[204:207], v[20:23]
	v_mfma_f32_16x16x32_bf16 v[16:19], v[176:179], v[200:203], v[16:19]
	v_mfma_f32_16x16x32_bf16 v[16:19], v[180:183], v[204:207], v[16:19]
	v_mfma_f32_16x16x32_bf16 v[4:7], v[168:171], v[208:211], v[4:7]
	v_mfma_f32_16x16x32_bf16 v[4:7], v[172:175], v[212:215], v[4:7]
	s_setprio 3
	s_barrier
	v_mfma_f32_16x16x32_bf16 v[0:3], v[176:179], v[208:211], v[0:3]
	v_mfma_f32_16x16x32_bf16 v[0:3], v[180:183], v[212:215], v[0:3]
	s_setprio 0
	s_add_i32 s50, s50, 2
	s_add_u32 s14, s14, 0x100
	s_addc_u32 s15, s15, 0
	s_add_u32 s48, s48, 0x100
	s_addc_u32 s49, s49, 0
	s_cmpk_gt_u32 s50, 0xfd
	s_cbranch_scc0 .LBB0_350
	s_and_b64 vcc, exec, s[10:11]
	s_cbranch_vccz .LBB0_353
	s_barrier
